# sigmoid epilogues (gate GEMM, GLU GEMM): 1/(1+e) via v_rcp_f32 instead of the IEEE div_scale/fmas chain; plus attention LDS prefetch
# speedup vs baseline: 1.0117x; 1.0117x over previous
.LBB0_1027:
	v_lshl_add_u32 v182, s26, 8, v162
	v_lshl_or_b32 v128, s27, 8, v187
	v_ashrrev_i32_e32 v183, 31, v182
	v_ashrrev_i32_e32 v129, 31, v128
	v_lshlrev_b64 v[180:181], 11, v[182:183]
	v_lshl_add_u64 v[130:131], s[6:7], 0, v[180:181]
	v_lshlrev_b64 v[178:179], 1, v[128:129]
	v_lshl_add_u64 v[20:21], v[128:129], 2, s[8:9]
	v_lshl_add_u64 v[128:129], v[130:131], 0, v[178:179]
	global_load_dwordx4 v[32:35], v[20:21], off offset:16
	global_load_dwordx4 v[36:39], v[20:21], off
	global_load_dwordx4 v[16:19], v[20:21], off offset:528
	s_nop 0
	global_load_dwordx4 v[20:23], v[20:21], off offset:512
	s_nop 0
	global_load_dwordx4 v[196:199], v[128:129], off
	global_load_dwordx4 v[152:155], v[128:129], off offset:256
	v_or_b32_e32 v128, 16, v182
	v_ashrrev_i32_e32 v129, 31, v128
	v_lshlrev_b64 v[184:185], 11, v[128:129]
	v_lshl_add_u64 v[128:129], s[6:7], 0, v[184:185]
	v_lshl_add_u64 v[128:129], v[128:129], 0, v[178:179]
	global_load_dwordx4 v[140:143], v[128:129], off
	s_nop 0
	global_load_dwordx4 v[128:131], v[128:129], off offset:256
	s_waitcnt vmcnt(0)
	v_pk_add_f32 v[148:149], v[148:149], v[36:37]
	v_lshlrev_b32_e32 v200, 16, v199
	v_mul_f32_e32 v148, 0xbfb8aa3b, v148
	v_exp_f32_e32 v148, v148
	v_and_b32_e32 v183, 0xffff0000, v199
	v_pk_add_f32 v[144:145], v[144:145], v[32:33]
	v_lshlrev_b32_e32 v192, 16, v196
	v_add_f32_e32 v148, 1.0, v148
	v_mul_f32_e32 v144, 0xbfb8aa3b, v144
	v_exp_f32_e32 v144, v144
	v_and_b32_e32 v195, 0xffff0000, v196
	v_rcp_f32_e32 v148, v148
	v_add_f32_e32 v144, 1.0, v144
	v_mul_f32_e32 v148, v148, v192
	v_lshlrev_b32_e32 v196, 16, v197
	v_and_b32_e32 v189, 0xffff0000, v197
	v_lshlrev_b32_e32 v197, 16, v198
	v_rcp_f32_e32 v144, v144
	s_nop 0
	v_mul_f32_e32 v192, v144, v197
	v_mul_f32_e32 v144, 0xbfb8aa3b, v149
	v_exp_f32_e32 v144, v144
	v_and_b32_e32 v198, 0xffff0000, v198
	v_pk_add_f32 v[150:151], v[150:151], v[38:39]
	v_pk_add_f32 v[146:147], v[146:147], v[34:35]
	v_add_f32_e32 v144, 1.0, v144
	v_pk_add_f32 v[136:137], v[136:137], v[20:21]
	v_pk_add_f32 v[138:139], v[138:139], v[22:23]
	v_pk_add_f32 v[134:135], v[134:135], v[18:19]
	v_rcp_f32_e32 v144, v144
	s_nop 0
	v_mul_f32_e32 v149, v144, v195
	v_mul_f32_e32 v144, 0xbfb8aa3b, v145
	v_exp_f32_e32 v144, v144
	v_mul_f32_e32 v138, 0xbfb8aa3b, v138
	v_exp_f32_e32 v138, v138
	v_mul_f32_e32 v134, 0xbfb8aa3b, v134
	v_add_f32_e32 v144, 1.0, v144
	v_add_f32_e32 v138, 1.0, v138
	v_exp_f32_e32 v134, v134
	v_mul_f32_e32 v135, 0xbfb8aa3b, v135
	v_rcp_f32_e32 v144, v144
	s_nop 0
	v_mul_f32_e32 v195, v144, v198
	v_mul_f32_e32 v144, 0xbfb8aa3b, v150
	v_exp_f32_e32 v144, v144
	v_add_f32_e32 v134, 1.0, v134
	v_exp_f32_e32 v135, v135
	v_pk_add_f32 v[124:125], v[124:125], v[36:37]
	v_add_f32_e32 v144, 1.0, v144
	v_add_f32_e32 v135, 1.0, v135
	v_mul_f32_e32 v124, 0xbfb8aa3b, v124
	v_exp_f32_e32 v124, v124
	v_rcp_f32_e32 v144, v144
	s_nop 0
	v_mul_f32_e32 v150, v144, v196
	v_mul_f32_e32 v144, 0xbfb8aa3b, v146
	v_exp_f32_e32 v144, v144
	v_add_f32_e32 v124, 1.0, v124
	v_pk_add_f32 v[120:121], v[120:121], v[32:33]
	v_pk_add_f32 v[126:127], v[126:127], v[38:39]
	v_add_f32_e32 v144, 1.0, v144
	v_mul_f32_e32 v120, 0xbfb8aa3b, v120
	v_exp_f32_e32 v120, v120
	v_pk_add_f32 v[122:123], v[122:123], v[34:35]
	v_rcp_f32_e32 v144, v144
	s_nop 0
	v_mul_f32_e32 v196, v144, v200
	v_mul_f32_e32 v144, 0xbfb8aa3b, v151
	v_exp_f32_e32 v144, v144
	v_add_f32_e32 v120, 1.0, v120
	v_pk_add_f32 v[116:117], v[116:117], v[20:21]
	v_pk_add_f32 v[118:119], v[118:119], v[22:23]
	v_add_f32_e32 v144, 1.0, v144
	v_mul_f32_e32 v118, 0xbfb8aa3b, v118
	v_exp_f32_e32 v118, v118
	v_pk_add_f32 v[114:115], v[114:115], v[18:19]
	v_rcp_f32_e32 v144, v144
	s_nop 0
	v_mul_f32_e32 v151, v144, v189
	v_mul_f32_e32 v144, 0xbfb8aa3b, v147
	v_exp_f32_e32 v144, v144
	v_add_f32_e32 v118, 1.0, v118
	v_mul_f32_e32 v114, 0xbfb8aa3b, v114
	v_exp_f32_e32 v114, v114
	v_add_f32_e32 v144, 1.0, v144
	v_add_f32_e32 v114, 1.0, v114
	v_mul_f32_e32 v115, 0xbfb8aa3b, v115
	v_exp_f32_e32 v115, v115
	v_rcp_f32_e32 v144, v144
	s_nop 0
	v_mul_f32_e32 v183, v144, v183
	v_lshl_add_u64 v[144:145], s[4:5], 0, v[180:181]
	v_lshl_add_u64 v[144:145], v[144:145], 0, v[178:179]
	v_cvt_pk_bf16_f32 v146, v148, v149
	v_cvt_pk_bf16_f32 v147, v150, v151
	v_cvt_pk_bf16_f32 v148, v192, v195
	v_cvt_pk_bf16_f32 v149, v196, v183
	global_store_dwordx4 v[144:145], v[146:149], off
	v_lshlrev_b32_e32 v183, 16, v155
	v_lshlrev_b32_e32 v150, 16, v152
	v_pk_add_f32 v[148:149], v[132:133], v[16:17]
	v_mul_f32_e32 v132, 0xbfb8aa3b, v136
	v_exp_f32_e32 v132, v132
	v_and_b32_e32 v146, 0xffff0000, v155
	v_and_b32_e32 v151, 0xffff0000, v152
	v_lshlrev_b32_e32 v152, 16, v153
	v_add_f32_e32 v132, 1.0, v132
	v_and_b32_e32 v147, 0xffff0000, v153
	v_lshlrev_b32_e32 v153, 16, v154
	v_and_b32_e32 v154, 0xffff0000, v154
	v_rcp_f32_e32 v132, v132
	v_mul_f32_e32 v133, 0xbfb8aa3b, v148
	v_exp_f32_e32 v133, v133
	v_mul_f32_e32 v132, v132, v150
	v_add_f32_e32 v115, 1.0, v115
	v_add_f32_e32 v133, 1.0, v133
	s_nop 0
	v_rcp_f32_e32 v133, v133
	s_nop 0
	v_mul_f32_e32 v136, v133, v153
	v_mul_f32_e32 v133, 0xbfb8aa3b, v137
	v_exp_f32_e32 v133, v133
	s_nop 0
	v_add_f32_e32 v133, 1.0, v133
	s_nop 0
	v_rcp_f32_e32 v133, v133
	v_mul_f32_e32 v137, 0xbfb8aa3b, v149
	v_exp_f32_e32 v137, v137
	v_mul_f32_e32 v133, v133, v151
	v_cvt_pk_bf16_f32 v132, v132, v133
	v_add_f32_e32 v137, 1.0, v137
	s_nop 0
	v_rcp_f32_e32 v137, v137
	s_nop 0
	v_mul_f32_e32 v137, v137, v154
	v_rcp_f32_e32 v138, v138
	s_nop 0
	v_mul_f32_e32 v138, v138, v152
	v_rcp_f32_e32 v134, v134
	s_nop 0
	v_mul_f32_e32 v148, v134, v183
	v_mul_f32_e32 v134, 0xbfb8aa3b, v139
	v_exp_f32_e32 v134, v134
	s_nop 0
	v_add_f32_e32 v134, 1.0, v134
	s_nop 0
	v_rcp_f32_e32 v134, v134
	s_nop 0
	v_mul_f32_e32 v134, v134, v147
	v_cvt_pk_bf16_f32 v133, v138, v134
	v_cvt_pk_bf16_f32 v134, v136, v137
	v_lshlrev_b32_e32 v136, 16, v141
	v_rcp_f32_e32 v135, v135
	s_nop 0
	v_mul_f32_e32 v135, v135, v146
	v_cvt_pk_bf16_f32 v135, v148, v135
	global_store_dwordx4 v[144:145], v[132:135], off offset:256
	v_lshlrev_b32_e32 v137, 16, v142
	v_and_b32_e32 v138, 0xffff0000, v142
	v_lshlrev_b32_e32 v134, 16, v140
	v_and_b32_e32 v135, 0xffff0000, v140
	v_and_b32_e32 v133, 0xffff0000, v141
	v_lshlrev_b32_e32 v139, 16, v143
	v_and_b32_e32 v132, 0xffff0000, v143
	v_rcp_f32_e32 v124, v124
	s_nop 0
	v_mul_f32_e32 v124, v124, v134
	s_nop 0
	v_rcp_f32_e32 v120, v120
	s_nop 0
	v_mul_f32_e32 v134, v120, v137
	v_mul_f32_e32 v120, 0xbfb8aa3b, v125
	v_exp_f32_e32 v120, v120
	s_nop 0
	v_add_f32_e32 v120, 1.0, v120
	s_nop 0
	v_rcp_f32_e32 v120, v120
	s_nop 0
	v_mul_f32_e32 v125, v120, v135
	v_mul_f32_e32 v120, 0xbfb8aa3b, v121
	v_exp_f32_e32 v120, v120
	s_nop 0
	v_add_f32_e32 v120, 1.0, v120
	s_nop 0
	v_rcp_f32_e32 v120, v120
	s_nop 0
	v_mul_f32_e32 v135, v120, v138
	v_mul_f32_e32 v120, 0xbfb8aa3b, v126
	v_exp_f32_e32 v120, v120
	s_nop 0
	v_add_f32_e32 v120, 1.0, v120
	s_nop 0
	v_rcp_f32_e32 v120, v120
	s_nop 0
	v_mul_f32_e32 v126, v120, v136
	v_mul_f32_e32 v120, 0xbfb8aa3b, v122
	v_exp_f32_e32 v120, v120
	s_nop 0
	v_add_f32_e32 v120, 1.0, v120
	s_nop 0
	v_rcp_f32_e32 v120, v120
	s_nop 0
	v_mul_f32_e32 v136, v120, v139
	v_mul_f32_e32 v120, 0xbfb8aa3b, v127
	v_exp_f32_e32 v120, v120
	s_nop 0
	v_add_f32_e32 v120, 1.0, v120
	s_nop 0
	v_rcp_f32_e32 v120, v120
	s_nop 0
	v_mul_f32_e32 v127, v120, v133
	v_mul_f32_e32 v120, 0xbfb8aa3b, v123
	v_exp_f32_e32 v120, v120
	s_nop 0
	v_add_f32_e32 v120, 1.0, v120
	s_nop 0
	v_rcp_f32_e32 v120, v120
	s_nop 0
	v_mul_f32_e32 v132, v120, v132
	v_lshl_add_u64 v[120:121], s[4:5], 0, v[184:185]
	v_lshl_add_u64 v[120:121], v[120:121], 0, v[178:179]
	v_cvt_pk_bf16_f32 v122, v124, v125
	v_cvt_pk_bf16_f32 v123, v126, v127
	v_cvt_pk_bf16_f32 v124, v134, v135
	v_cvt_pk_bf16_f32 v125, v136, v132
	global_store_dwordx4 v[120:121], v[122:125], off
	v_lshlrev_b32_e32 v132, 16, v131
	v_lshlrev_b32_e32 v126, 16, v128
	v_pk_add_f32 v[124:125], v[112:113], v[16:17]
	v_mul_f32_e32 v112, 0xbfb8aa3b, v116
	v_exp_f32_e32 v112, v112
	v_and_b32_e32 v122, 0xffff0000, v131
	v_and_b32_e32 v127, 0xffff0000, v128
	v_lshlrev_b32_e32 v128, 16, v129
	v_add_f32_e32 v112, 1.0, v112
	v_and_b32_e32 v123, 0xffff0000, v129
	v_lshlrev_b32_e32 v129, 16, v130
	v_and_b32_e32 v130, 0xffff0000, v130
	v_rcp_f32_e32 v112, v112
	v_mul_f32_e32 v113, 0xbfb8aa3b, v124
	v_exp_f32_e32 v113, v113
	v_mul_f32_e32 v112, v112, v126
	v_add_f32_e32 v113, 1.0, v113
	s_nop 0
	v_rcp_f32_e32 v113, v113
	s_nop 0
	v_mul_f32_e32 v116, v113, v129
	v_mul_f32_e32 v113, 0xbfb8aa3b, v117
	v_exp_f32_e32 v113, v113
	s_nop 0
	v_add_f32_e32 v113, 1.0, v113
	s_nop 0
	v_rcp_f32_e32 v113, v113
	v_mul_f32_e32 v117, 0xbfb8aa3b, v125
	v_exp_f32_e32 v117, v117
	v_mul_f32_e32 v113, v113, v127
	v_cvt_pk_bf16_f32 v112, v112, v113
	v_add_f32_e32 v117, 1.0, v117
	s_nop 0
	v_rcp_f32_e32 v117, v117
	s_nop 0
	v_mul_f32_e32 v117, v117, v130
	v_rcp_f32_e32 v118, v118
	s_nop 0
	v_mul_f32_e32 v118, v118, v128
	v_rcp_f32_e32 v114, v114
	s_nop 0
	v_mul_f32_e32 v124, v114, v132
	v_mul_f32_e32 v114, 0xbfb8aa3b, v119
	v_exp_f32_e32 v114, v114
	s_nop 0
	v_add_f32_e32 v114, 1.0, v114
	s_nop 0
	v_rcp_f32_e32 v114, v114
	s_nop 0
	v_mul_f32_e32 v114, v114, v123
	v_cvt_pk_bf16_f32 v113, v118, v114
	v_cvt_pk_bf16_f32 v114, v116, v117
	s_nop 0
	v_rcp_f32_e32 v115, v115
	s_nop 0
	v_mul_f32_e32 v115, v115, v122
	v_cvt_pk_bf16_f32 v115, v124, v115
	global_store_dwordx4 v[120:121], v[112:115], off offset:256
	s_nop 1
	s_nop 1
	v_or_b32_e32 v112, 32, v182
	v_ashrrev_i32_e32 v113, 31, v112
	v_lshlrev_b64 v[126:127], 11, v[112:113]
	v_lshl_add_u64 v[112:113], s[6:7], 0, v[126:127]
	v_lshl_add_u64 v[112:113], v[112:113], 0, v[178:179]
	global_load_dwordx4 v[128:131], v[112:113], off
	global_load_dwordx4 v[120:123], v[112:113], off offset:256
	v_or_b32_e32 v112, 48, v182
	v_ashrrev_i32_e32 v113, 31, v112
	v_lshlrev_b64 v[124:125], 11, v[112:113]
	v_lshl_add_u64 v[112:113], s[6:7], 0, v[124:125]
	v_lshl_add_u64 v[112:113], v[112:113], 0, v[178:179]
	global_load_dwordx4 v[116:119], v[112:113], off
	s_nop 0
	global_load_dwordx4 v[112:115], v[112:113], off offset:256
	v_pk_add_f32 v[108:109], v[108:109], v[36:37]
	s_waitcnt vmcnt(3)
	v_lshlrev_b32_e32 v132, 16, v128
	v_mul_f32_e32 v108, 0xbfb8aa3b, v108
	v_exp_f32_e32 v108, v108
	v_and_b32_e32 v133, 0xffff0000, v128
	v_lshlrev_b32_e32 v136, 16, v131
	v_and_b32_e32 v128, 0xffff0000, v131
	v_add_f32_e32 v108, 1.0, v108
	v_pk_add_f32 v[104:105], v[104:105], v[32:33]
	v_lshlrev_b32_e32 v135, 16, v130
	v_mul_f32_e32 v104, 0xbfb8aa3b, v104
	v_exp_f32_e32 v104, v104
	s_nop 0
	v_add_f32_e32 v104, 1.0, v104
	v_rcp_f32_e32 v108, v108
	s_nop 0
	v_mul_f32_e32 v108, v108, v132
	v_and_b32_e32 v130, 0xffff0000, v130
	v_pk_add_f32 v[110:111], v[110:111], v[38:39]
	v_lshlrev_b32_e32 v134, 16, v129
	v_rcp_f32_e32 v104, v104
	s_nop 0
	v_mul_f32_e32 v131, v104, v135
	v_mul_f32_e32 v104, 0xbfb8aa3b, v109
	v_exp_f32_e32 v104, v104
	v_pk_add_f32 v[106:107], v[106:107], v[34:35]
	v_and_b32_e32 v129, 0xffff0000, v129
	v_pk_add_f32 v[100:101], v[100:101], v[20:21]
	v_add_f32_e32 v104, 1.0, v104
	v_pk_add_f32 v[102:103], v[102:103], v[22:23]
	v_pk_add_f32 v[98:99], v[98:99], v[18:19]
	v_mul_f32_e32 v102, 0xbfb8aa3b, v102
	v_rcp_f32_e32 v104, v104
	s_nop 0
	v_mul_f32_e32 v109, v104, v133
	v_mul_f32_e32 v104, 0xbfb8aa3b, v105
	v_exp_f32_e32 v104, v104
	v_exp_f32_e32 v102, v102
	v_mul_f32_e32 v98, 0xbfb8aa3b, v98
	v_exp_f32_e32 v98, v98
	v_add_f32_e32 v104, 1.0, v104
	v_add_f32_e32 v102, 1.0, v102
	v_add_f32_e32 v98, 1.0, v98
	v_mul_f32_e32 v99, 0xbfb8aa3b, v99
	v_rcp_f32_e32 v104, v104
	s_nop 0
	v_mul_f32_e32 v130, v104, v130
	v_mul_f32_e32 v104, 0xbfb8aa3b, v110
	v_exp_f32_e32 v104, v104
	v_exp_f32_e32 v99, v99
	v_pk_add_f32 v[92:93], v[92:93], v[36:37]
	v_pk_add_f32 v[88:89], v[88:89], v[32:33]
	v_add_f32_e32 v104, 1.0, v104
	v_add_f32_e32 v99, 1.0, v99
	v_mul_f32_e32 v92, 0xbfb8aa3b, v92
	v_exp_f32_e32 v92, v92
	v_rcp_f32_e32 v104, v104
	s_nop 0
	v_mul_f32_e32 v110, v104, v134
	v_mul_f32_e32 v104, 0xbfb8aa3b, v106
	v_exp_f32_e32 v104, v104
	v_add_f32_e32 v92, 1.0, v92
	v_mul_f32_e32 v88, 0xbfb8aa3b, v88
	v_exp_f32_e32 v88, v88
	v_add_f32_e32 v104, 1.0, v104
	v_add_f32_e32 v88, 1.0, v88
	v_pk_add_f32 v[94:95], v[94:95], v[38:39]
	v_pk_add_f32 v[90:91], v[90:91], v[34:35]
	v_rcp_f32_e32 v104, v104
	s_nop 0
	v_mul_f32_e32 v132, v104, v136
	v_mul_f32_e32 v104, 0xbfb8aa3b, v111
	v_exp_f32_e32 v104, v104
	v_pk_add_f32 v[84:85], v[84:85], v[20:21]
	v_pk_add_f32 v[86:87], v[86:87], v[22:23]
	v_pk_add_f32 v[82:83], v[82:83], v[18:19]
	v_add_f32_e32 v104, 1.0, v104
	v_mul_f32_e32 v86, 0xbfb8aa3b, v86
	v_exp_f32_e32 v86, v86
	v_mul_f32_e32 v82, 0xbfb8aa3b, v82
	v_rcp_f32_e32 v104, v104
	s_nop 0
	v_mul_f32_e32 v111, v104, v129
	v_mul_f32_e32 v104, 0xbfb8aa3b, v107
	v_exp_f32_e32 v104, v104
	v_add_f32_e32 v86, 1.0, v86
	v_exp_f32_e32 v82, v82
	v_mul_f32_e32 v83, 0xbfb8aa3b, v83
	v_add_f32_e32 v104, 1.0, v104
	v_add_f32_e32 v82, 1.0, v82
	v_exp_f32_e32 v83, v83
	v_rcp_f32_e32 v104, v104
	s_nop 0
	v_mul_f32_e32 v128, v104, v128
	v_lshl_add_u64 v[104:105], s[4:5], 0, v[126:127]
	v_lshl_add_u64 v[104:105], v[104:105], 0, v[178:179]
	v_cvt_pk_bf16_f32 v106, v108, v109
	v_cvt_pk_bf16_f32 v107, v110, v111
	v_cvt_pk_bf16_f32 v108, v131, v130
	v_cvt_pk_bf16_f32 v109, v132, v128
	global_store_dwordx4 v[104:105], v[106:109], off
	s_waitcnt vmcnt(3)
	v_lshlrev_b32_e32 v126, 16, v123
	v_lshlrev_b32_e32 v110, 16, v120
	v_pk_add_f32 v[108:109], v[96:97], v[16:17]
	v_mul_f32_e32 v96, 0xbfb8aa3b, v100
	v_exp_f32_e32 v96, v96
	v_and_b32_e32 v106, 0xffff0000, v123
	v_and_b32_e32 v111, 0xffff0000, v120
	v_lshlrev_b32_e32 v120, 16, v121
	v_add_f32_e32 v96, 1.0, v96
	v_and_b32_e32 v107, 0xffff0000, v121
	v_lshlrev_b32_e32 v121, 16, v122
	v_and_b32_e32 v122, 0xffff0000, v122
	v_rcp_f32_e32 v96, v96
	v_mul_f32_e32 v97, 0xbfb8aa3b, v108
	v_exp_f32_e32 v97, v97
	v_mul_f32_e32 v96, v96, v110
	v_add_f32_e32 v83, 1.0, v83
	v_add_f32_e32 v97, 1.0, v97
	s_nop 0
	v_rcp_f32_e32 v97, v97
	s_nop 0
	v_mul_f32_e32 v100, v97, v121
	v_mul_f32_e32 v97, 0xbfb8aa3b, v101
	v_exp_f32_e32 v97, v97
	s_nop 0
	v_add_f32_e32 v97, 1.0, v97
	s_nop 0
	v_rcp_f32_e32 v97, v97
	v_mul_f32_e32 v101, 0xbfb8aa3b, v109
	v_exp_f32_e32 v101, v101
	v_mul_f32_e32 v97, v97, v111
	v_cvt_pk_bf16_f32 v96, v96, v97
	v_add_f32_e32 v101, 1.0, v101
	s_nop 0
	v_rcp_f32_e32 v101, v101
	s_nop 0
	v_mul_f32_e32 v101, v101, v122
	v_rcp_f32_e32 v102, v102
	s_nop 0
	v_mul_f32_e32 v102, v102, v120
	v_rcp_f32_e32 v98, v98
	s_nop 0
	v_mul_f32_e32 v108, v98, v126
	v_mul_f32_e32 v98, 0xbfb8aa3b, v103
	v_exp_f32_e32 v98, v98
	s_nop 0
	v_add_f32_e32 v98, 1.0, v98
	s_nop 0
	v_rcp_f32_e32 v98, v98
	s_nop 0
	v_mul_f32_e32 v98, v98, v107
	v_cvt_pk_bf16_f32 v97, v102, v98
	v_cvt_pk_bf16_f32 v98, v100, v101
	s_waitcnt vmcnt(2)
	v_lshlrev_b32_e32 v101, 16, v118
	v_rcp_f32_e32 v99, v99
	s_nop 0
	v_mul_f32_e32 v99, v99, v106
	v_cvt_pk_bf16_f32 v99, v108, v99
	global_store_dwordx4 v[104:105], v[96:99], off offset:256
	s_nop 1
	v_lshlrev_b32_e32 v98, 16, v116
	v_and_b32_e32 v99, 0xffff0000, v116
	v_and_b32_e32 v102, 0xffff0000, v118
	v_rcp_f32_e32 v92, v92
	s_nop 0
	v_mul_f32_e32 v92, v92, v98
	v_lshlrev_b32_e32 v100, 16, v117
	v_lshlrev_b32_e32 v103, 16, v119
	v_and_b32_e32 v97, 0xffff0000, v117
	v_rcp_f32_e32 v88, v88
	s_nop 0
	v_mul_f32_e32 v98, v88, v101
	v_mul_f32_e32 v88, 0xbfb8aa3b, v93
	v_exp_f32_e32 v88, v88
	v_and_b32_e32 v96, 0xffff0000, v119
	v_add_f32_e32 v88, 1.0, v88
	s_nop 0
	v_rcp_f32_e32 v88, v88
	s_nop 0
	v_mul_f32_e32 v93, v88, v99
	v_mul_f32_e32 v88, 0xbfb8aa3b, v89
	v_exp_f32_e32 v88, v88
	s_nop 0
	v_add_f32_e32 v88, 1.0, v88
	s_nop 0
	v_rcp_f32_e32 v88, v88
	s_nop 0
	v_mul_f32_e32 v99, v88, v102
	v_mul_f32_e32 v88, 0xbfb8aa3b, v94
	v_exp_f32_e32 v88, v88
	s_nop 0
	v_add_f32_e32 v88, 1.0, v88
	s_nop 0
	v_rcp_f32_e32 v88, v88
	s_nop 0
	v_mul_f32_e32 v94, v88, v100
	v_mul_f32_e32 v88, 0xbfb8aa3b, v90
	v_exp_f32_e32 v88, v88
	s_nop 0
	v_add_f32_e32 v88, 1.0, v88
	s_nop 0
	v_rcp_f32_e32 v88, v88
	s_nop 0
	v_mul_f32_e32 v100, v88, v103
	v_mul_f32_e32 v88, 0xbfb8aa3b, v95
	v_exp_f32_e32 v88, v88
	s_nop 0
	v_add_f32_e32 v88, 1.0, v88
	s_nop 0
	v_rcp_f32_e32 v88, v88
	s_nop 0
	v_mul_f32_e32 v95, v88, v97
	v_mul_f32_e32 v88, 0xbfb8aa3b, v91
	v_exp_f32_e32 v88, v88
	s_nop 0
	v_add_f32_e32 v88, 1.0, v88
	s_nop 0
	v_rcp_f32_e32 v88, v88
	s_nop 0
	v_mul_f32_e32 v96, v88, v96
	v_lshl_add_u64 v[88:89], s[4:5], 0, v[124:125]
	v_lshl_add_u64 v[88:89], v[88:89], 0, v[178:179]
	v_cvt_pk_bf16_f32 v90, v92, v93
	v_cvt_pk_bf16_f32 v91, v94, v95
	v_cvt_pk_bf16_f32 v92, v98, v99
	v_cvt_pk_bf16_f32 v93, v100, v96
	global_store_dwordx4 v[88:89], v[90:93], off
	s_waitcnt vmcnt(3)
	v_lshlrev_b32_e32 v94, 16, v112
	v_lshlrev_b32_e32 v97, 16, v114
	v_pk_add_f32 v[92:93], v[80:81], v[16:17]
	v_mul_f32_e32 v80, 0xbfb8aa3b, v84
	v_exp_f32_e32 v80, v80
	v_and_b32_e32 v95, 0xffff0000, v112
	v_lshlrev_b32_e32 v96, 16, v113
	v_lshlrev_b32_e32 v99, 16, v115
	v_add_f32_e32 v80, 1.0, v80
	v_and_b32_e32 v91, 0xffff0000, v113
	v_and_b32_e32 v90, 0xffff0000, v115
	v_and_b32_e32 v98, 0xffff0000, v114
	v_rcp_f32_e32 v80, v80
	v_mul_f32_e32 v81, 0xbfb8aa3b, v92
	v_exp_f32_e32 v81, v81
	v_mul_f32_e32 v80, v80, v94
	v_add_f32_e32 v81, 1.0, v81
	s_nop 0
	v_rcp_f32_e32 v81, v81
	s_nop 0
	v_mul_f32_e32 v84, v81, v97
	v_mul_f32_e32 v81, 0xbfb8aa3b, v85
	v_exp_f32_e32 v81, v81
	s_nop 0
	v_add_f32_e32 v81, 1.0, v81
	s_nop 0
	v_rcp_f32_e32 v81, v81
	v_mul_f32_e32 v85, 0xbfb8aa3b, v93
	v_exp_f32_e32 v85, v85
	v_mul_f32_e32 v81, v81, v95
	v_cvt_pk_bf16_f32 v80, v80, v81
	v_add_f32_e32 v85, 1.0, v85
	s_nop 0
	v_rcp_f32_e32 v85, v85
	s_nop 0
	v_mul_f32_e32 v85, v85, v98
	v_rcp_f32_e32 v86, v86
	s_nop 0
	v_mul_f32_e32 v86, v86, v96
	v_rcp_f32_e32 v82, v82
	s_nop 0
	v_mul_f32_e32 v92, v82, v99
	v_mul_f32_e32 v82, 0xbfb8aa3b, v87
	v_exp_f32_e32 v82, v82
	s_nop 0
	v_add_f32_e32 v82, 1.0, v82
	s_nop 0
	v_rcp_f32_e32 v82, v82
	s_nop 0
	v_mul_f32_e32 v82, v82, v91
	v_cvt_pk_bf16_f32 v81, v86, v82
	v_cvt_pk_bf16_f32 v82, v84, v85
	s_nop 0
	v_rcp_f32_e32 v83, v83
	s_nop 0
	v_mul_f32_e32 v83, v83, v90
	v_cvt_pk_bf16_f32 v83, v92, v83
	global_store_dwordx4 v[88:89], v[80:83], off offset:256
	s_mov_b64 s[26:27], 0x40000
	v_lshl_add_u64 v[94:95], v[180:181], 0, s[26:27]
	v_lshl_add_u64 v[80:81], s[6:7], 0, v[94:95]
	s_mov_b64 s[26:27], 0x48000
	v_lshl_add_u64 v[80:81], v[80:81], 0, v[178:179]
	v_lshl_add_u64 v[92:93], v[180:181], 0, s[26:27]
	global_load_dwordx4 v[96:99], v[80:81], off
	global_load_dwordx4 v[88:91], v[80:81], off offset:256
	v_lshl_add_u64 v[80:81], s[6:7], 0, v[92:93]
	v_lshl_add_u64 v[80:81], v[80:81], 0, v[178:179]
	global_load_dwordx4 v[84:87], v[80:81], off
	s_nop 0
	global_load_dwordx4 v[80:83], v[80:81], off offset:256
	v_pk_add_f32 v[76:77], v[76:77], v[36:37]
	s_waitcnt vmcnt(3)
	v_lshlrev_b32_e32 v100, 16, v96
	v_mul_f32_e32 v76, 0xbfb8aa3b, v76
	v_exp_f32_e32 v76, v76
	v_and_b32_e32 v101, 0xffff0000, v96
	v_lshlrev_b32_e32 v104, 16, v99
	v_and_b32_e32 v96, 0xffff0000, v99
	v_add_f32_e32 v76, 1.0, v76
	v_pk_add_f32 v[72:73], v[72:73], v[32:33]
	v_lshlrev_b32_e32 v103, 16, v98
	v_mul_f32_e32 v72, 0xbfb8aa3b, v72
	v_exp_f32_e32 v72, v72
	s_nop 0
	v_add_f32_e32 v72, 1.0, v72
	v_rcp_f32_e32 v76, v76
	s_nop 0
	v_mul_f32_e32 v76, v76, v100
	v_and_b32_e32 v98, 0xffff0000, v98
	v_pk_add_f32 v[78:79], v[78:79], v[38:39]
	v_lshlrev_b32_e32 v102, 16, v97
	v_rcp_f32_e32 v72, v72
	s_nop 0
	v_mul_f32_e32 v99, v72, v103
	v_mul_f32_e32 v72, 0xbfb8aa3b, v77
	v_exp_f32_e32 v72, v72
	v_pk_add_f32 v[74:75], v[74:75], v[34:35]
	v_and_b32_e32 v97, 0xffff0000, v97
	v_pk_add_f32 v[68:69], v[68:69], v[20:21]
	v_add_f32_e32 v72, 1.0, v72
	v_pk_add_f32 v[70:71], v[70:71], v[22:23]
	v_pk_add_f32 v[66:67], v[66:67], v[18:19]
	v_mul_f32_e32 v70, 0xbfb8aa3b, v70
	v_rcp_f32_e32 v72, v72
	s_nop 0
	v_mul_f32_e32 v77, v72, v101
	v_mul_f32_e32 v72, 0xbfb8aa3b, v73
	v_exp_f32_e32 v72, v72
	v_exp_f32_e32 v70, v70
	v_mul_f32_e32 v66, 0xbfb8aa3b, v66
	v_exp_f32_e32 v66, v66
	v_add_f32_e32 v72, 1.0, v72
	v_add_f32_e32 v70, 1.0, v70
	v_add_f32_e32 v66, 1.0, v66
	v_mul_f32_e32 v67, 0xbfb8aa3b, v67
	v_rcp_f32_e32 v72, v72
	s_nop 0
	v_mul_f32_e32 v98, v72, v98
	v_mul_f32_e32 v72, 0xbfb8aa3b, v78
	v_exp_f32_e32 v72, v72
	v_exp_f32_e32 v67, v67
	v_pk_add_f32 v[60:61], v[60:61], v[36:37]
	v_pk_add_f32 v[56:57], v[56:57], v[32:33]
	v_add_f32_e32 v72, 1.0, v72
	v_add_f32_e32 v67, 1.0, v67
	v_mul_f32_e32 v60, 0xbfb8aa3b, v60
	v_exp_f32_e32 v60, v60
	v_rcp_f32_e32 v72, v72
	s_nop 0
	v_mul_f32_e32 v78, v72, v102
	v_mul_f32_e32 v72, 0xbfb8aa3b, v74
	v_exp_f32_e32 v72, v72
	v_add_f32_e32 v60, 1.0, v60
	v_mul_f32_e32 v56, 0xbfb8aa3b, v56
	v_exp_f32_e32 v56, v56
	v_add_f32_e32 v72, 1.0, v72
	v_add_f32_e32 v56, 1.0, v56
	v_pk_add_f32 v[62:63], v[62:63], v[38:39]
	v_pk_add_f32 v[58:59], v[58:59], v[34:35]
	v_rcp_f32_e32 v72, v72
	s_nop 0
	v_mul_f32_e32 v100, v72, v104
	v_mul_f32_e32 v72, 0xbfb8aa3b, v79
	v_exp_f32_e32 v72, v72
	v_pk_add_f32 v[52:53], v[52:53], v[20:21]
	v_pk_add_f32 v[54:55], v[54:55], v[22:23]
	v_pk_add_f32 v[50:51], v[50:51], v[18:19]
	v_add_f32_e32 v72, 1.0, v72
	v_mul_f32_e32 v54, 0xbfb8aa3b, v54
	v_exp_f32_e32 v54, v54
	v_mul_f32_e32 v50, 0xbfb8aa3b, v50
	v_rcp_f32_e32 v72, v72
	s_nop 0
	v_mul_f32_e32 v79, v72, v97
	v_mul_f32_e32 v72, 0xbfb8aa3b, v75
	v_exp_f32_e32 v72, v72
	v_add_f32_e32 v54, 1.0, v54
	v_exp_f32_e32 v50, v50
	v_mul_f32_e32 v51, 0xbfb8aa3b, v51
	v_add_f32_e32 v72, 1.0, v72
	v_add_f32_e32 v50, 1.0, v50
	v_exp_f32_e32 v51, v51
	v_rcp_f32_e32 v72, v72
	s_nop 0
	v_mul_f32_e32 v96, v72, v96
	v_lshl_add_u64 v[72:73], s[4:5], 0, v[94:95]
	v_lshl_add_u64 v[72:73], v[72:73], 0, v[178:179]
	v_cvt_pk_bf16_f32 v74, v76, v77
	v_cvt_pk_bf16_f32 v75, v78, v79
	v_cvt_pk_bf16_f32 v76, v99, v98
	v_cvt_pk_bf16_f32 v77, v100, v96
	global_store_dwordx4 v[72:73], v[74:77], off
	s_waitcnt vmcnt(3)
	v_lshlrev_b32_e32 v94, 16, v91
	v_lshlrev_b32_e32 v78, 16, v88
	v_pk_add_f32 v[76:77], v[64:65], v[16:17]
	v_mul_f32_e32 v64, 0xbfb8aa3b, v68
	v_exp_f32_e32 v64, v64
	v_and_b32_e32 v74, 0xffff0000, v91
	v_and_b32_e32 v79, 0xffff0000, v88
	v_lshlrev_b32_e32 v88, 16, v89
	v_add_f32_e32 v64, 1.0, v64
	v_and_b32_e32 v75, 0xffff0000, v89
	v_lshlrev_b32_e32 v89, 16, v90
	v_and_b32_e32 v90, 0xffff0000, v90
	v_rcp_f32_e32 v64, v64
	v_mul_f32_e32 v65, 0xbfb8aa3b, v76
	v_exp_f32_e32 v65, v65
	v_mul_f32_e32 v64, v64, v78
	v_add_f32_e32 v51, 1.0, v51
	v_add_f32_e32 v65, 1.0, v65
	s_nop 0
	v_rcp_f32_e32 v65, v65
	s_nop 0
	v_mul_f32_e32 v68, v65, v89
	v_mul_f32_e32 v65, 0xbfb8aa3b, v69
	v_exp_f32_e32 v65, v65
	s_nop 0
	v_add_f32_e32 v65, 1.0, v65
	s_nop 0
	v_rcp_f32_e32 v65, v65
	v_mul_f32_e32 v69, 0xbfb8aa3b, v77
	v_exp_f32_e32 v69, v69
	v_mul_f32_e32 v65, v65, v79
	v_cvt_pk_bf16_f32 v64, v64, v65
	v_add_f32_e32 v69, 1.0, v69
	s_nop 0
	v_rcp_f32_e32 v69, v69
	s_nop 0
	v_mul_f32_e32 v69, v69, v90
	v_rcp_f32_e32 v70, v70
	s_nop 0
	v_mul_f32_e32 v70, v70, v88
	v_rcp_f32_e32 v66, v66
	s_nop 0
	v_mul_f32_e32 v76, v66, v94
	v_mul_f32_e32 v66, 0xbfb8aa3b, v71
	v_exp_f32_e32 v66, v66
	s_nop 0
	v_add_f32_e32 v66, 1.0, v66
	s_nop 0
	v_rcp_f32_e32 v66, v66
	s_nop 0
	v_mul_f32_e32 v66, v66, v75
	v_cvt_pk_bf16_f32 v65, v70, v66
	v_cvt_pk_bf16_f32 v66, v68, v69
	s_waitcnt vmcnt(2)
	v_lshlrev_b32_e32 v69, 16, v86
	v_rcp_f32_e32 v67, v67
	s_nop 0
	v_mul_f32_e32 v67, v67, v74
	v_cvt_pk_bf16_f32 v67, v76, v67
	global_store_dwordx4 v[72:73], v[64:67], off offset:256
	s_nop 1
	v_lshlrev_b32_e32 v66, 16, v84
	v_and_b32_e32 v67, 0xffff0000, v84
	v_and_b32_e32 v70, 0xffff0000, v86
	v_rcp_f32_e32 v60, v60
	s_nop 0
	v_mul_f32_e32 v60, v60, v66
	v_lshlrev_b32_e32 v68, 16, v85
	v_lshlrev_b32_e32 v71, 16, v87
	v_and_b32_e32 v65, 0xffff0000, v85
	v_rcp_f32_e32 v56, v56
	s_nop 0
	v_mul_f32_e32 v66, v56, v69
	v_mul_f32_e32 v56, 0xbfb8aa3b, v61
	v_exp_f32_e32 v56, v56
	v_and_b32_e32 v64, 0xffff0000, v87
	v_add_f32_e32 v56, 1.0, v56
	s_nop 0
	v_rcp_f32_e32 v56, v56
	s_nop 0
	v_mul_f32_e32 v61, v56, v67
	v_mul_f32_e32 v56, 0xbfb8aa3b, v57
	v_exp_f32_e32 v56, v56
	s_nop 0
	v_add_f32_e32 v56, 1.0, v56
	s_nop 0
	v_rcp_f32_e32 v56, v56
	s_nop 0
	v_mul_f32_e32 v67, v56, v70
	v_mul_f32_e32 v56, 0xbfb8aa3b, v62
	v_exp_f32_e32 v56, v56
	s_nop 0
	v_add_f32_e32 v56, 1.0, v56
	s_nop 0
	v_rcp_f32_e32 v56, v56
	s_nop 0
	v_mul_f32_e32 v62, v56, v68
	v_mul_f32_e32 v56, 0xbfb8aa3b, v58
	v_exp_f32_e32 v56, v56
	s_nop 0
	v_add_f32_e32 v56, 1.0, v56
	s_nop 0
	v_rcp_f32_e32 v56, v56
	s_nop 0
	v_mul_f32_e32 v68, v56, v71
	v_mul_f32_e32 v56, 0xbfb8aa3b, v63
	v_exp_f32_e32 v56, v56
	s_nop 0
	v_add_f32_e32 v56, 1.0, v56
	s_nop 0
	v_rcp_f32_e32 v56, v56
	s_nop 0
	v_mul_f32_e32 v63, v56, v65
	v_mul_f32_e32 v56, 0xbfb8aa3b, v59
	v_exp_f32_e32 v56, v56
	s_nop 0
	v_add_f32_e32 v56, 1.0, v56
	s_nop 0
	v_rcp_f32_e32 v56, v56
	s_nop 0
	v_mul_f32_e32 v64, v56, v64
	v_lshl_add_u64 v[56:57], s[4:5], 0, v[92:93]
	v_lshl_add_u64 v[56:57], v[56:57], 0, v[178:179]
	v_cvt_pk_bf16_f32 v58, v60, v61
	v_cvt_pk_bf16_f32 v59, v62, v63
	v_cvt_pk_bf16_f32 v60, v66, v67
	v_cvt_pk_bf16_f32 v61, v68, v64
	global_store_dwordx4 v[56:57], v[58:61], off
	s_waitcnt vmcnt(3)
	v_lshlrev_b32_e32 v62, 16, v80
	v_lshlrev_b32_e32 v65, 16, v82
	v_pk_add_f32 v[60:61], v[48:49], v[16:17]
	v_mul_f32_e32 v48, 0xbfb8aa3b, v52
	v_exp_f32_e32 v48, v48
	v_and_b32_e32 v63, 0xffff0000, v80
	v_lshlrev_b32_e32 v64, 16, v81
	v_lshlrev_b32_e32 v67, 16, v83
	v_add_f32_e32 v48, 1.0, v48
	v_and_b32_e32 v59, 0xffff0000, v81
	v_and_b32_e32 v58, 0xffff0000, v83
	v_and_b32_e32 v66, 0xffff0000, v82
	v_rcp_f32_e32 v48, v48
	v_mul_f32_e32 v49, 0xbfb8aa3b, v60
	v_exp_f32_e32 v49, v49
	v_mul_f32_e32 v48, v48, v62
	v_add_f32_e32 v49, 1.0, v49
	s_nop 0
	v_rcp_f32_e32 v49, v49
	s_nop 0
	v_mul_f32_e32 v52, v49, v65
	v_mul_f32_e32 v49, 0xbfb8aa3b, v53
	v_exp_f32_e32 v49, v49
	s_nop 0
	v_add_f32_e32 v49, 1.0, v49
	s_nop 0
	v_rcp_f32_e32 v49, v49
	v_mul_f32_e32 v53, 0xbfb8aa3b, v61
	v_exp_f32_e32 v53, v53
	v_mul_f32_e32 v49, v49, v63
	v_cvt_pk_bf16_f32 v48, v48, v49
	v_add_f32_e32 v53, 1.0, v53
	s_nop 0
	v_rcp_f32_e32 v53, v53
	s_nop 0
	v_mul_f32_e32 v53, v53, v66
	v_rcp_f32_e32 v54, v54
	s_nop 0
	v_mul_f32_e32 v54, v54, v64
	v_rcp_f32_e32 v50, v50
	s_nop 0
	v_mul_f32_e32 v60, v50, v67
	v_mul_f32_e32 v50, 0xbfb8aa3b, v55
	v_exp_f32_e32 v50, v50
	s_nop 0
	v_add_f32_e32 v50, 1.0, v50
	s_nop 0
	v_rcp_f32_e32 v50, v50
	s_nop 0
	v_mul_f32_e32 v50, v50, v59
	v_cvt_pk_bf16_f32 v49, v54, v50
	v_cvt_pk_bf16_f32 v50, v52, v53
	s_nop 0
	v_rcp_f32_e32 v51, v51
	s_nop 0
	v_mul_f32_e32 v51, v51, v58
	v_cvt_pk_bf16_f32 v51, v60, v51
	global_store_dwordx4 v[56:57], v[48:51], off offset:256
	s_mov_b64 s[26:27], 0x50000
	v_lshl_add_u64 v[62:63], v[180:181], 0, s[26:27]
	v_lshl_add_u64 v[48:49], s[6:7], 0, v[62:63]
	s_mov_b64 s[26:27], 0x58000
	v_lshl_add_u64 v[48:49], v[48:49], 0, v[178:179]
	v_lshl_add_u64 v[60:61], v[180:181], 0, s[26:27]
	global_load_dwordx4 v[64:67], v[48:49], off
	global_load_dwordx4 v[56:59], v[48:49], off offset:256
	v_lshl_add_u64 v[48:49], s[6:7], 0, v[60:61]
	v_lshl_add_u64 v[48:49], v[48:49], 0, v[178:179]
	global_load_dwordx4 v[52:55], v[48:49], off
	s_nop 0
	global_load_dwordx4 v[48:51], v[48:49], off offset:256
	v_pk_add_f32 v[44:45], v[44:45], v[36:37]
	s_waitcnt vmcnt(3)
	v_lshlrev_b32_e32 v68, 16, v64
	v_mul_f32_e32 v44, 0xbfb8aa3b, v44
	v_exp_f32_e32 v44, v44
	v_and_b32_e32 v69, 0xffff0000, v64
	v_lshlrev_b32_e32 v72, 16, v67
	v_and_b32_e32 v64, 0xffff0000, v67
	v_add_f32_e32 v44, 1.0, v44
	v_pk_add_f32 v[40:41], v[40:41], v[32:33]
	v_lshlrev_b32_e32 v71, 16, v66
	v_mul_f32_e32 v40, 0xbfb8aa3b, v40
	v_exp_f32_e32 v40, v40
	s_nop 0
	v_add_f32_e32 v40, 1.0, v40
	v_rcp_f32_e32 v44, v44
	s_nop 0
	v_mul_f32_e32 v44, v44, v68
	v_and_b32_e32 v66, 0xffff0000, v66
	v_pk_add_f32 v[46:47], v[46:47], v[38:39]
	v_lshlrev_b32_e32 v70, 16, v65
	v_rcp_f32_e32 v40, v40
	s_nop 0
	v_mul_f32_e32 v67, v40, v71
	v_mul_f32_e32 v40, 0xbfb8aa3b, v45
	v_exp_f32_e32 v40, v40
	v_pk_add_f32 v[42:43], v[42:43], v[34:35]
	v_and_b32_e32 v65, 0xffff0000, v65
	v_pk_add_f32 v[28:29], v[28:29], v[20:21]
	v_add_f32_e32 v40, 1.0, v40
	v_pk_add_f32 v[30:31], v[30:31], v[22:23]
	v_pk_add_f32 v[26:27], v[26:27], v[18:19]
	v_mul_f32_e32 v30, 0xbfb8aa3b, v30
	v_rcp_f32_e32 v40, v40
	s_nop 0
	v_mul_f32_e32 v45, v40, v69
	v_mul_f32_e32 v40, 0xbfb8aa3b, v41
	v_exp_f32_e32 v40, v40
	v_exp_f32_e32 v30, v30
	v_mul_f32_e32 v26, 0xbfb8aa3b, v26
	v_exp_f32_e32 v26, v26
	v_add_f32_e32 v40, 1.0, v40
	v_add_f32_e32 v30, 1.0, v30
	v_add_f32_e32 v26, 1.0, v26
	v_mul_f32_e32 v27, 0xbfb8aa3b, v27
	v_rcp_f32_e32 v40, v40
	s_nop 0
	v_mul_f32_e32 v66, v40, v66
	v_mul_f32_e32 v40, 0xbfb8aa3b, v46
	v_exp_f32_e32 v40, v40
	v_exp_f32_e32 v27, v27
	v_pk_add_f32 v[12:13], v[12:13], v[36:37]
	v_pk_add_f32 v[8:9], v[8:9], v[32:33]
	v_add_f32_e32 v40, 1.0, v40
	v_add_f32_e32 v27, 1.0, v27
	v_mul_f32_e32 v12, 0xbfb8aa3b, v12
	v_exp_f32_e32 v12, v12
	v_rcp_f32_e32 v40, v40
	s_nop 0
	v_mul_f32_e32 v46, v40, v70
	v_mul_f32_e32 v40, 0xbfb8aa3b, v42
	v_exp_f32_e32 v40, v40
	v_add_f32_e32 v12, 1.0, v12
	v_add_f32_e32 v40, 1.0, v40
	v_pk_add_f32 v[10:11], v[10:11], v[34:35]
	v_mul_f32_e32 v8, 0xbfb8aa3b, v8
	v_rcp_f32_e32 v40, v40
	s_nop 0
	v_mul_f32_e32 v68, v40, v72
	v_mul_f32_e32 v40, 0xbfb8aa3b, v47
	v_exp_f32_e32 v40, v40
	v_exp_f32_e32 v8, v8
	v_add_f32_e32 v40, 1.0, v40
	v_add_f32_e32 v8, 1.0, v8
	v_pk_add_f32 v[14:15], v[14:15], v[38:39]
	v_pk_add_f32 v[4:5], v[4:5], v[20:21]
	v_rcp_f32_e32 v40, v40
	s_nop 0
	v_mul_f32_e32 v47, v40, v65
	v_mul_f32_e32 v40, 0xbfb8aa3b, v43
	v_exp_f32_e32 v40, v40
	v_pk_add_f32 v[2:3], v[2:3], v[18:19]
	v_pk_add_f32 v[6:7], v[6:7], v[22:23]
	v_mul_f32_e32 v2, 0xbfb8aa3b, v2
	v_add_f32_e32 v40, 1.0, v40
	v_mul_f32_e32 v6, 0xbfb8aa3b, v6
	v_exp_f32_e32 v6, v6
	v_exp_f32_e32 v2, v2
	v_rcp_f32_e32 v40, v40
	s_nop 0
	v_mul_f32_e32 v64, v40, v64
	v_lshl_add_u64 v[40:41], s[4:5], 0, v[62:63]
	v_lshl_add_u64 v[40:41], v[40:41], 0, v[178:179]
	v_cvt_pk_bf16_f32 v42, v44, v45
	v_cvt_pk_bf16_f32 v43, v46, v47
	v_cvt_pk_bf16_f32 v44, v67, v66
	v_cvt_pk_bf16_f32 v45, v68, v64
	global_store_dwordx4 v[40:41], v[42:45], off
	s_waitcnt vmcnt(3)
	v_lshlrev_b32_e32 v62, 16, v59
	v_lshlrev_b32_e32 v46, 16, v56
	v_pk_add_f32 v[44:45], v[24:25], v[16:17]
	v_mul_f32_e32 v24, 0xbfb8aa3b, v28
	v_exp_f32_e32 v24, v24
	v_and_b32_e32 v42, 0xffff0000, v59
	v_and_b32_e32 v47, 0xffff0000, v56
	v_lshlrev_b32_e32 v56, 16, v57
	v_add_f32_e32 v24, 1.0, v24
	v_and_b32_e32 v43, 0xffff0000, v57
	v_lshlrev_b32_e32 v57, 16, v58
	v_and_b32_e32 v58, 0xffff0000, v58
	v_rcp_f32_e32 v24, v24
	v_mul_f32_e32 v25, 0xbfb8aa3b, v44
	v_exp_f32_e32 v25, v25
	v_mul_f32_e32 v24, v24, v46
	v_add_f32_e32 v6, 1.0, v6
	v_add_f32_e32 v2, 1.0, v2
	v_add_f32_e32 v25, 1.0, v25
	v_mul_f32_e32 v3, 0xbfb8aa3b, v3
	v_exp_f32_e32 v3, v3
	v_rcp_f32_e32 v25, v25
	s_nop 0
	v_mul_f32_e32 v28, v25, v57
	v_mul_f32_e32 v25, 0xbfb8aa3b, v29
	v_exp_f32_e32 v25, v25
	v_add_f32_e32 v3, 1.0, v3
	v_add_f32_e32 v25, 1.0, v25
	s_nop 0
	v_rcp_f32_e32 v25, v25
	v_mul_f32_e32 v29, 0xbfb8aa3b, v45
	v_exp_f32_e32 v29, v29
	v_mul_f32_e32 v25, v25, v47
	v_cvt_pk_bf16_f32 v24, v24, v25
	v_add_f32_e32 v29, 1.0, v29
	s_nop 0
	v_rcp_f32_e32 v29, v29
	s_nop 0
	v_mul_f32_e32 v29, v29, v58
	v_rcp_f32_e32 v30, v30
	s_nop 0
	v_mul_f32_e32 v30, v30, v56
	v_rcp_f32_e32 v26, v26
	s_nop 0
	v_mul_f32_e32 v44, v26, v62
	v_mul_f32_e32 v26, 0xbfb8aa3b, v31
	v_exp_f32_e32 v26, v26
	s_nop 0
	v_add_f32_e32 v26, 1.0, v26
	s_nop 0
	v_rcp_f32_e32 v26, v26
	s_nop 0
	v_mul_f32_e32 v26, v26, v43
	v_cvt_pk_bf16_f32 v25, v30, v26
	v_cvt_pk_bf16_f32 v26, v28, v29
	s_waitcnt vmcnt(2)
	v_lshlrev_b32_e32 v29, 16, v54
	v_rcp_f32_e32 v27, v27
	s_nop 0
	v_mul_f32_e32 v27, v27, v42
	v_cvt_pk_bf16_f32 v27, v44, v27
	global_store_dwordx4 v[40:41], v[24:27], off offset:256
	v_rcp_f32_e32 v12, v12
	v_and_b32_e32 v30, 0xffff0000, v54
	v_lshlrev_b32_e32 v26, 16, v52
	v_mul_f32_e32 v12, v12, v26
	v_and_b32_e32 v27, 0xffff0000, v52
	v_lshlrev_b32_e32 v28, 16, v53
	v_lshlrev_b32_e32 v31, 16, v55
	v_rcp_f32_e32 v8, v8
	s_nop 0
	v_mul_f32_e32 v26, v8, v29
	v_mul_f32_e32 v8, 0xbfb8aa3b, v13
	v_exp_f32_e32 v8, v8
	v_and_b32_e32 v25, 0xffff0000, v53
	v_and_b32_e32 v24, 0xffff0000, v55
	v_add_f32_e32 v8, 1.0, v8
	s_nop 0
	v_rcp_f32_e32 v8, v8
	s_nop 0
	v_mul_f32_e32 v13, v8, v27
	v_mul_f32_e32 v8, 0xbfb8aa3b, v9
	v_exp_f32_e32 v8, v8
	s_nop 0
	v_add_f32_e32 v8, 1.0, v8
	s_nop 0
	v_rcp_f32_e32 v8, v8
	s_nop 0
	v_mul_f32_e32 v27, v8, v30
	v_mul_f32_e32 v8, 0xbfb8aa3b, v14
	v_exp_f32_e32 v8, v8
	s_nop 0
	v_add_f32_e32 v8, 1.0, v8
	s_nop 0
	v_rcp_f32_e32 v8, v8
	s_nop 0
	v_mul_f32_e32 v14, v8, v28
	v_mul_f32_e32 v8, 0xbfb8aa3b, v10
	v_exp_f32_e32 v8, v8
	s_nop 0
	v_add_f32_e32 v8, 1.0, v8
	s_nop 0
	v_rcp_f32_e32 v8, v8
	s_nop 0
	v_mul_f32_e32 v28, v8, v31
	v_mul_f32_e32 v8, 0xbfb8aa3b, v15
	v_exp_f32_e32 v8, v8
	s_nop 0
	v_add_f32_e32 v8, 1.0, v8
	s_nop 0
	v_rcp_f32_e32 v8, v8
	s_nop 0
	v_mul_f32_e32 v15, v8, v25
	v_mul_f32_e32 v8, 0xbfb8aa3b, v11
	v_exp_f32_e32 v8, v8
	s_nop 0
	v_add_f32_e32 v8, 1.0, v8
	s_nop 0
	v_rcp_f32_e32 v8, v8
	s_nop 0
	v_mul_f32_e32 v24, v8, v24
	v_lshl_add_u64 v[8:9], s[4:5], 0, v[60:61]
	v_lshl_add_u64 v[8:9], v[8:9], 0, v[178:179]
	v_cvt_pk_bf16_f32 v10, v12, v13
	v_cvt_pk_bf16_f32 v11, v14, v15
	v_cvt_pk_bf16_f32 v12, v26, v27
	v_cvt_pk_bf16_f32 v13, v28, v24
	global_store_dwordx4 v[8:9], v[10:13], off
	s_waitcnt vmcnt(3)
	v_lshlrev_b32_e32 v14, 16, v48
	v_lshlrev_b32_e32 v25, 16, v50
	v_pk_add_f32 v[12:13], v[0:1], v[16:17]
	v_mul_f32_e32 v0, 0xbfb8aa3b, v4
	v_exp_f32_e32 v0, v0
	v_and_b32_e32 v15, 0xffff0000, v48
	v_lshlrev_b32_e32 v27, 16, v51
	v_and_b32_e32 v11, 0xffff0000, v49
	v_add_f32_e32 v0, 1.0, v0
	v_and_b32_e32 v10, 0xffff0000, v51
	v_lshlrev_b32_e32 v24, 16, v49
	v_and_b32_e32 v26, 0xffff0000, v50
	v_rcp_f32_e32 v0, v0
	v_mul_f32_e32 v1, 0xbfb8aa3b, v12
	v_exp_f32_e32 v1, v1
	v_mul_f32_e32 v0, v0, v14
	v_add_f32_e32 v1, 1.0, v1
	s_nop 0
	v_rcp_f32_e32 v1, v1
	s_nop 0
	v_mul_f32_e32 v4, v1, v25
	v_mul_f32_e32 v1, 0xbfb8aa3b, v5
	v_exp_f32_e32 v1, v1
	s_nop 0
	v_add_f32_e32 v1, 1.0, v1
	s_nop 0
	v_rcp_f32_e32 v1, v1
	v_mul_f32_e32 v5, 0xbfb8aa3b, v13
	v_exp_f32_e32 v5, v5
	v_mul_f32_e32 v1, v1, v15
	v_cvt_pk_bf16_f32 v0, v0, v1
	v_add_f32_e32 v5, 1.0, v5
	s_nop 0
	v_rcp_f32_e32 v5, v5
	s_nop 0
	v_mul_f32_e32 v5, v5, v26
	v_rcp_f32_e32 v6, v6
	s_nop 0
	v_mul_f32_e32 v6, v6, v24
	v_rcp_f32_e32 v2, v2
	s_nop 0
	v_mul_f32_e32 v12, v2, v27
	v_mul_f32_e32 v2, 0xbfb8aa3b, v7
	v_exp_f32_e32 v2, v2
	s_nop 0
	v_add_f32_e32 v2, 1.0, v2
	s_nop 0
	v_rcp_f32_e32 v2, v2
	s_nop 0
	v_mul_f32_e32 v2, v2, v11
	v_cvt_pk_bf16_f32 v1, v6, v2
	v_cvt_pk_bf16_f32 v2, v4, v5
	s_nop 0
	v_rcp_f32_e32 v3, v3
	s_nop 0
	v_mul_f32_e32 v3, v3, v10
	v_cvt_pk_bf16_f32 v3, v12, v3
	global_store_dwordx4 v[8:9], v[0:3], off offset:256
	s_andn2_b64 vcc, exec, s[38:39]
	s_mov_b64 s[26:27], -1
	s_cbranch_vccnz .LBB0_1020
	s_andn2_b64 vcc, exec, s[2:3]
	s_cbranch_vccnz .LBB0_1019
	s_barrier
	s_branch .LBB0_1019

.LBB0_1100:
	v_lshl_or_b32 v154, s19, 8, v158
	v_ashrrev_i32_e32 v155, 31, v154
	v_lshl_add_u64 v[16:17], v[154:155], 2, s[6:7]
	global_load_dwordx4 v[32:35], v[16:17], off offset:16
	global_load_dwordx4 v[36:39], v[16:17], off
	v_or_b32_e32 v16, 0x80, v154
	v_ashrrev_i32_e32 v17, 31, v16
	v_lshl_add_u64 v[20:21], v[16:17], 2, s[6:7]
	global_load_dwordx4 v[16:19], v[20:21], off offset:16
	s_nop 0
	global_load_dwordx4 v[20:23], v[20:21], off
	v_lshl_add_u32 v162, s18, 8, v156
	s_waitcnt vmcnt(0)
	v_pk_add_f32 v[140:141], v[140:141], v[36:37]
	v_pk_add_f32 v[136:137], v[136:137], v[32:33]
	v_mul_f32_e32 v140, 0xbfb8aa3b, v140
	v_exp_f32_e32 v140, v140
	v_mul_f32_e32 v136, 0xbfb8aa3b, v136
	v_exp_f32_e32 v136, v136
	v_pk_add_f32 v[142:143], v[142:143], v[38:39]
	v_add_f32_e32 v140, 1.0, v140
	v_add_f32_e32 v136, 1.0, v136
	v_pk_add_f32 v[138:139], v[138:139], v[34:35]
	v_pk_add_f32 v[132:133], v[132:133], v[20:21]
	v_rcp_f32_e32 v172, v140
	v_mul_f32_e32 v132, 0xbfb8aa3b, v132
	v_exp_f32_e32 v132, v132
	s_movk_i32 s11, 0x3000
	v_rcp_f32_e32 v174, v136
	v_mul_f32_e32 v136, 0xbfb8aa3b, v141
	v_exp_f32_e32 v136, v136
	v_add_f32_e32 v132, 1.0, v132
	v_pk_add_f32 v[128:129], v[128:129], v[16:17]
	v_pk_add_f32 v[134:135], v[134:135], v[22:23]
	v_add_f32_e32 v136, 1.0, v136
	v_mul_f32_e32 v128, 0xbfb8aa3b, v128
	v_exp_f32_e32 v128, v128
	v_mul_f32_e32 v129, 0xbfb8aa3b, v129
	v_rcp_f32_e32 v173, v136
	v_mul_f32_e32 v136, 0xbfb8aa3b, v137
	v_exp_f32_e32 v136, v136
	v_cvt_pk_bf16_f32 v172, v172, v173
	v_add_f32_e32 v128, 1.0, v128
	v_exp_f32_e32 v129, v129
	v_add_f32_e32 v136, 1.0, v136
	v_add_f32_e32 v129, 1.0, v129
	v_pk_add_f32 v[130:131], v[130:131], v[18:19]
	v_pk_add_f32 v[124:125], v[124:125], v[36:37]
	v_rcp_f32_e32 v175, v136
	v_mul_f32_e32 v136, 0xbfb8aa3b, v142
	v_exp_f32_e32 v136, v136
	v_mul_f32_e32 v130, 0xbfb8aa3b, v130
	v_exp_f32_e32 v130, v130
	v_mul_f32_e32 v131, 0xbfb8aa3b, v131
	v_add_f32_e32 v136, 1.0, v136
	v_add_f32_e32 v130, 1.0, v130
	v_exp_f32_e32 v131, v131
	v_mul_f32_e32 v124, 0xbfb8aa3b, v124
	v_rcp_f32_e32 v142, v136
	v_mul_f32_e32 v136, 0xbfb8aa3b, v138
	v_exp_f32_e32 v136, v136
	v_add_f32_e32 v131, 1.0, v131
	v_exp_f32_e32 v124, v124
	v_pk_add_f32 v[120:121], v[120:121], v[32:33]
	v_add_f32_e32 v136, 1.0, v136
	v_add_f32_e32 v124, 1.0, v124
	v_mul_f32_e32 v120, 0xbfb8aa3b, v120
	v_exp_f32_e32 v120, v120
	v_rcp_f32_e32 v176, v136
	v_mul_f32_e32 v136, 0xbfb8aa3b, v143
	v_exp_f32_e32 v136, v136
	v_add_f32_e32 v120, 1.0, v120
	v_pk_add_f32 v[126:127], v[126:127], v[38:39]
	v_pk_add_f32 v[122:123], v[122:123], v[34:35]
	v_add_f32_e32 v136, 1.0, v136
	v_pk_add_f32 v[116:117], v[116:117], v[20:21]
	v_pk_add_f32 v[112:113], v[112:113], v[16:17]
	v_mul_f32_e32 v116, 0xbfb8aa3b, v116
	v_rcp_f32_e32 v143, v136
	v_mul_f32_e32 v136, 0xbfb8aa3b, v139
	v_exp_f32_e32 v136, v136
	v_cvt_pk_bf16_f32 v173, v142, v143
	v_add_f32_e32 v136, 1.0, v136
	v_cvt_pk_bf16_f32 v174, v174, v175
	v_exp_f32_e32 v116, v116
	v_rcp_f32_e32 v177, v136
	v_mov_b64_e32 v[136:137], s[4:5]
	v_lshlrev_b64 v[138:139], 1, v[154:155]
	v_mad_i64_i32 v[140:141], s[18:19], v162, s11, v[136:137]
	v_lshl_add_u64 v[140:141], v[140:141], 0, v[138:139]
	v_cvt_pk_bf16_f32 v175, v176, v177
	global_store_dwordx4 v[140:141], v[172:175], off
	v_add_f32_e32 v116, 1.0, v116
	v_mul_f32_e32 v112, 0xbfb8aa3b, v112
	v_rcp_f32_e32 v132, v132
	v_exp_f32_e32 v112, v112
	v_mul_f32_e32 v113, 0xbfb8aa3b, v113
	v_exp_f32_e32 v113, v113
	v_rcp_f32_e32 v142, v128
	v_mul_f32_e32 v128, 0xbfb8aa3b, v133
	v_exp_f32_e32 v128, v128
	v_add_f32_e32 v112, 1.0, v112
	v_add_f32_e32 v113, 1.0, v113
	v_pk_add_f32 v[118:119], v[118:119], v[22:23]
	v_add_f32_e32 v128, 1.0, v128
	v_pk_add_f32 v[114:115], v[114:115], v[18:19]
	v_rcp_f32_e32 v128, v128
	s_nop 0
	v_cvt_pk_bf16_f32 v128, v132, v128
	v_mul_f32_e32 v114, 0xbfb8aa3b, v114
	v_exp_f32_e32 v114, v114
	v_rcp_f32_e32 v133, v129
	v_mul_f32_e32 v129, 0xbfb8aa3b, v134
	v_exp_f32_e32 v129, v129
	v_add_f32_e32 v114, 1.0, v114
	v_mul_f32_e32 v115, 0xbfb8aa3b, v115
	v_exp_f32_e32 v115, v115
	v_add_f32_e32 v129, 1.0, v129
	v_add_f32_e32 v115, 1.0, v115
	v_rcp_f32_e32 v129, v129
	s_nop 0
	v_rcp_f32_e32 v134, v130
	v_mul_f32_e32 v130, 0xbfb8aa3b, v135
	v_exp_f32_e32 v130, v130
	s_nop 0
	v_add_f32_e32 v130, 1.0, v130
	s_nop 0
	v_rcp_f32_e32 v130, v130
	s_nop 0
	v_cvt_pk_bf16_f32 v129, v129, v130
	v_cvt_pk_bf16_f32 v130, v142, v133
	s_nop 0
	v_rcp_f32_e32 v131, v131
	s_nop 0
	v_cvt_pk_bf16_f32 v131, v134, v131
	global_store_dwordx4 v[140:141], v[128:131], off offset:256
	s_nop 1
	s_nop 1
	v_or_b32_e32 v128, 16, v162
	v_rcp_f32_e32 v124, v124
	s_nop 0
	v_rcp_f32_e32 v129, v120
	v_mul_f32_e32 v120, 0xbfb8aa3b, v125
	v_exp_f32_e32 v120, v120
	s_nop 0
	v_add_f32_e32 v120, 1.0, v120
	s_nop 0
	v_rcp_f32_e32 v125, v120
	v_mul_f32_e32 v120, 0xbfb8aa3b, v121
	v_exp_f32_e32 v120, v120
	s_nop 0
	v_add_f32_e32 v120, 1.0, v120
	s_nop 0
	v_rcp_f32_e32 v130, v120
	v_mul_f32_e32 v120, 0xbfb8aa3b, v126
	v_exp_f32_e32 v120, v120
	s_nop 0
	v_add_f32_e32 v120, 1.0, v120
	s_nop 0
	v_rcp_f32_e32 v126, v120
	v_mul_f32_e32 v120, 0xbfb8aa3b, v122
	v_exp_f32_e32 v120, v120
	s_nop 0
	v_add_f32_e32 v120, 1.0, v120
	s_nop 0
	v_rcp_f32_e32 v131, v120
	v_mul_f32_e32 v120, 0xbfb8aa3b, v127
	v_exp_f32_e32 v120, v120
	s_nop 0
	v_add_f32_e32 v120, 1.0, v120
	s_nop 0
	v_rcp_f32_e32 v127, v120
	v_mul_f32_e32 v120, 0xbfb8aa3b, v123
	v_exp_f32_e32 v120, v120
	s_nop 0
	v_add_f32_e32 v120, 1.0, v120
	s_nop 0
	v_rcp_f32_e32 v132, v120
	v_mad_i64_i32 v[120:121], s[18:19], v128, s11, v[136:137]
	v_lshl_add_u64 v[120:121], v[120:121], 0, v[138:139]
	v_cvt_pk_bf16_f32 v122, v124, v125
	v_cvt_pk_bf16_f32 v123, v126, v127
	v_cvt_pk_bf16_f32 v124, v129, v130
	v_cvt_pk_bf16_f32 v125, v131, v132
	global_store_dwordx4 v[120:121], v[122:125], off
	s_nop 1
	s_nop 0
	v_rcp_f32_e32 v116, v116
	s_nop 0
	v_rcp_f32_e32 v122, v112
	v_mul_f32_e32 v112, 0xbfb8aa3b, v117
	v_exp_f32_e32 v112, v112
	s_nop 0
	v_add_f32_e32 v112, 1.0, v112
	s_nop 0
	v_rcp_f32_e32 v112, v112
	s_nop 0
	v_cvt_pk_bf16_f32 v112, v116, v112
	s_nop 0
	v_rcp_f32_e32 v117, v113
	v_mul_f32_e32 v113, 0xbfb8aa3b, v118
	v_exp_f32_e32 v113, v113
	s_nop 0
	v_add_f32_e32 v113, 1.0, v113
	s_nop 0
	v_rcp_f32_e32 v113, v113
	s_nop 0
	v_rcp_f32_e32 v118, v114
	v_mul_f32_e32 v114, 0xbfb8aa3b, v119
	v_exp_f32_e32 v114, v114
	s_nop 0
	v_add_f32_e32 v114, 1.0, v114
	s_nop 0
	v_rcp_f32_e32 v114, v114
	s_nop 0
	v_cvt_pk_bf16_f32 v113, v113, v114
	v_cvt_pk_bf16_f32 v114, v122, v117
	s_nop 0
	v_rcp_f32_e32 v115, v115
	s_nop 0
	v_cvt_pk_bf16_f32 v115, v118, v115
	global_store_dwordx4 v[120:121], v[112:115], off offset:256
	v_pk_add_f32 v[108:109], v[108:109], v[36:37]
	v_pk_add_f32 v[104:105], v[104:105], v[32:33]
	v_mul_f32_e32 v108, 0xbfb8aa3b, v108
	v_exp_f32_e32 v108, v108
	v_mul_f32_e32 v104, 0xbfb8aa3b, v104
	v_exp_f32_e32 v104, v104
	v_pk_add_f32 v[110:111], v[110:111], v[38:39]
	v_add_f32_e32 v108, 1.0, v108
	v_add_f32_e32 v104, 1.0, v104
	v_pk_add_f32 v[106:107], v[106:107], v[34:35]
	v_pk_add_f32 v[100:101], v[100:101], v[20:21]
	v_rcp_f32_e32 v108, v108
	v_mul_f32_e32 v100, 0xbfb8aa3b, v100
	v_exp_f32_e32 v100, v100
	v_or_b32_e32 v112, 32, v162
	v_rcp_f32_e32 v113, v104
	v_mul_f32_e32 v104, 0xbfb8aa3b, v109
	v_exp_f32_e32 v104, v104
	v_add_f32_e32 v100, 1.0, v100
	v_pk_add_f32 v[96:97], v[96:97], v[16:17]
	v_pk_add_f32 v[102:103], v[102:103], v[22:23]
	v_add_f32_e32 v104, 1.0, v104
	v_mul_f32_e32 v96, 0xbfb8aa3b, v96
	v_exp_f32_e32 v96, v96
	v_mul_f32_e32 v97, 0xbfb8aa3b, v97
	v_rcp_f32_e32 v109, v104
	v_mul_f32_e32 v104, 0xbfb8aa3b, v105
	v_exp_f32_e32 v104, v104
	v_add_f32_e32 v96, 1.0, v96
	v_exp_f32_e32 v97, v97
	v_pk_add_f32 v[98:99], v[98:99], v[18:19]
	v_add_f32_e32 v104, 1.0, v104
	v_add_f32_e32 v97, 1.0, v97
	v_mul_f32_e32 v98, 0xbfb8aa3b, v98
	v_exp_f32_e32 v98, v98
	v_rcp_f32_e32 v114, v104
	v_mul_f32_e32 v104, 0xbfb8aa3b, v110
	v_exp_f32_e32 v104, v104
	v_add_f32_e32 v98, 1.0, v98
	v_mul_f32_e32 v99, 0xbfb8aa3b, v99
	v_exp_f32_e32 v99, v99
	v_add_f32_e32 v104, 1.0, v104
	v_add_f32_e32 v99, 1.0, v99
	v_pk_add_f32 v[92:93], v[92:93], v[36:37]
	v_pk_add_f32 v[88:89], v[88:89], v[32:33]
	v_rcp_f32_e32 v110, v104
	v_mul_f32_e32 v104, 0xbfb8aa3b, v106
	v_exp_f32_e32 v104, v104
	v_mul_f32_e32 v92, 0xbfb8aa3b, v92
	v_exp_f32_e32 v92, v92
	v_mul_f32_e32 v88, 0xbfb8aa3b, v88
	v_add_f32_e32 v104, 1.0, v104
	v_add_f32_e32 v92, 1.0, v92
	v_exp_f32_e32 v88, v88
	v_pk_add_f32 v[94:95], v[94:95], v[38:39]
	v_rcp_f32_e32 v115, v104
	v_mul_f32_e32 v104, 0xbfb8aa3b, v111
	v_exp_f32_e32 v104, v104
	v_add_f32_e32 v88, 1.0, v88
	v_pk_add_f32 v[90:91], v[90:91], v[34:35]
	v_pk_add_f32 v[84:85], v[84:85], v[20:21]
	v_add_f32_e32 v104, 1.0, v104
	v_mul_f32_e32 v84, 0xbfb8aa3b, v84
	v_exp_f32_e32 v84, v84
	v_pk_add_f32 v[80:81], v[80:81], v[16:17]
	v_rcp_f32_e32 v111, v104
	v_mul_f32_e32 v104, 0xbfb8aa3b, v107
	v_exp_f32_e32 v104, v104
	v_add_f32_e32 v84, 1.0, v84
	v_mul_f32_e32 v80, 0xbfb8aa3b, v80
	v_exp_f32_e32 v80, v80
	v_add_f32_e32 v104, 1.0, v104
	v_add_f32_e32 v80, 1.0, v80
	v_mul_f32_e32 v81, 0xbfb8aa3b, v81
	v_exp_f32_e32 v81, v81
	v_rcp_f32_e32 v116, v104
	v_mad_i64_i32 v[104:105], s[18:19], v112, s11, v[136:137]
	v_lshl_add_u64 v[104:105], v[104:105], 0, v[138:139]
	v_cvt_pk_bf16_f32 v106, v108, v109
	v_cvt_pk_bf16_f32 v107, v110, v111
	v_cvt_pk_bf16_f32 v108, v113, v114
	v_cvt_pk_bf16_f32 v109, v115, v116
	global_store_dwordx4 v[104:105], v[106:109], off
	v_add_f32_e32 v81, 1.0, v81
	v_pk_add_f32 v[86:87], v[86:87], v[22:23]
	v_pk_add_f32 v[82:83], v[82:83], v[18:19]
	v_rcp_f32_e32 v100, v100
	v_mul_f32_e32 v82, 0xbfb8aa3b, v82
	v_exp_f32_e32 v82, v82
	v_mul_f32_e32 v83, 0xbfb8aa3b, v83
	v_rcp_f32_e32 v106, v96
	v_mul_f32_e32 v96, 0xbfb8aa3b, v101
	v_exp_f32_e32 v96, v96
	v_add_f32_e32 v82, 1.0, v82
	v_exp_f32_e32 v83, v83
	v_add_f32_e32 v96, 1.0, v96
	v_add_f32_e32 v83, 1.0, v83
	v_rcp_f32_e32 v96, v96
	s_nop 0
	v_cvt_pk_bf16_f32 v96, v100, v96
	s_nop 0
	v_rcp_f32_e32 v101, v97
	v_mul_f32_e32 v97, 0xbfb8aa3b, v102
	v_exp_f32_e32 v97, v97
	s_nop 0
	v_add_f32_e32 v97, 1.0, v97
	s_nop 0
	v_rcp_f32_e32 v97, v97
	s_nop 0
	v_rcp_f32_e32 v102, v98
	v_mul_f32_e32 v98, 0xbfb8aa3b, v103
	v_exp_f32_e32 v98, v98
	s_nop 0
	v_add_f32_e32 v98, 1.0, v98
	s_nop 0
	v_rcp_f32_e32 v98, v98
	s_nop 0
	v_cvt_pk_bf16_f32 v97, v97, v98
	v_cvt_pk_bf16_f32 v98, v106, v101
	s_nop 0
	v_rcp_f32_e32 v99, v99
	s_nop 0
	v_cvt_pk_bf16_f32 v99, v102, v99
	global_store_dwordx4 v[104:105], v[96:99], off offset:256
	s_nop 1
	s_nop 1
	v_or_b32_e32 v96, 48, v162
	v_rcp_f32_e32 v92, v92
	s_nop 0
	v_rcp_f32_e32 v97, v88
	v_mul_f32_e32 v88, 0xbfb8aa3b, v93
	v_exp_f32_e32 v88, v88
	s_nop 0
	v_add_f32_e32 v88, 1.0, v88
	s_nop 0
	v_rcp_f32_e32 v93, v88
	v_mul_f32_e32 v88, 0xbfb8aa3b, v89
	v_exp_f32_e32 v88, v88
	s_nop 0
	v_add_f32_e32 v88, 1.0, v88
	s_nop 0
	v_rcp_f32_e32 v98, v88
	v_mul_f32_e32 v88, 0xbfb8aa3b, v94
	v_exp_f32_e32 v88, v88
	s_nop 0
	v_add_f32_e32 v88, 1.0, v88
	s_nop 0
	v_rcp_f32_e32 v94, v88
	v_mul_f32_e32 v88, 0xbfb8aa3b, v90
	v_exp_f32_e32 v88, v88
	s_nop 0
	v_add_f32_e32 v88, 1.0, v88
	s_nop 0
	v_rcp_f32_e32 v99, v88
	v_mul_f32_e32 v88, 0xbfb8aa3b, v95
	v_exp_f32_e32 v88, v88
	s_nop 0
	v_add_f32_e32 v88, 1.0, v88
	s_nop 0
	v_rcp_f32_e32 v95, v88
	v_mul_f32_e32 v88, 0xbfb8aa3b, v91
	v_exp_f32_e32 v88, v88
	s_nop 0
	v_add_f32_e32 v88, 1.0, v88
	s_nop 0
	v_rcp_f32_e32 v100, v88
	v_mad_i64_i32 v[88:89], s[18:19], v96, s11, v[136:137]
	v_lshl_add_u64 v[88:89], v[88:89], 0, v[138:139]
	v_cvt_pk_bf16_f32 v90, v92, v93
	v_cvt_pk_bf16_f32 v91, v94, v95
	v_cvt_pk_bf16_f32 v92, v97, v98
	v_cvt_pk_bf16_f32 v93, v99, v100
	global_store_dwordx4 v[88:89], v[90:93], off
	s_nop 1
	s_nop 0
	v_rcp_f32_e32 v84, v84
	s_nop 0
	v_rcp_f32_e32 v90, v80
	v_mul_f32_e32 v80, 0xbfb8aa3b, v85
	v_exp_f32_e32 v80, v80
	s_nop 0
	v_add_f32_e32 v80, 1.0, v80
	s_nop 0
	v_rcp_f32_e32 v80, v80
	s_nop 0
	v_cvt_pk_bf16_f32 v80, v84, v80
	s_nop 0
	v_rcp_f32_e32 v85, v81
	v_mul_f32_e32 v81, 0xbfb8aa3b, v86
	v_exp_f32_e32 v81, v81
	s_nop 0
	v_add_f32_e32 v81, 1.0, v81
	s_nop 0
	v_rcp_f32_e32 v81, v81
	s_nop 0
	v_rcp_f32_e32 v86, v82
	v_mul_f32_e32 v82, 0xbfb8aa3b, v87
	v_exp_f32_e32 v82, v82
	s_nop 0
	v_add_f32_e32 v82, 1.0, v82
	s_nop 0
	v_rcp_f32_e32 v82, v82
	s_nop 0
	v_cvt_pk_bf16_f32 v81, v81, v82
	v_cvt_pk_bf16_f32 v82, v90, v85
	s_nop 0
	v_rcp_f32_e32 v83, v83
	s_nop 0
	v_cvt_pk_bf16_f32 v83, v86, v83
	global_store_dwordx4 v[88:89], v[80:83], off offset:256
	s_nop 1
	s_nop 1
	v_add_u32_e32 v80, 0x80, v162
	v_pk_add_f32 v[76:77], v[76:77], v[36:37]
	v_pk_add_f32 v[72:73], v[72:73], v[32:33]
	v_mul_f32_e32 v76, 0xbfb8aa3b, v76
	v_exp_f32_e32 v76, v76
	v_mul_f32_e32 v72, 0xbfb8aa3b, v72
	v_exp_f32_e32 v72, v72
	v_pk_add_f32 v[78:79], v[78:79], v[38:39]
	v_add_f32_e32 v76, 1.0, v76
	v_add_f32_e32 v72, 1.0, v72
	v_pk_add_f32 v[74:75], v[74:75], v[34:35]
	v_pk_add_f32 v[68:69], v[68:69], v[20:21]
	v_rcp_f32_e32 v76, v76
	v_mul_f32_e32 v68, 0xbfb8aa3b, v68
	v_exp_f32_e32 v68, v68
	v_pk_add_f32 v[64:65], v[64:65], v[16:17]
	v_rcp_f32_e32 v81, v72
	v_mul_f32_e32 v72, 0xbfb8aa3b, v77
	v_exp_f32_e32 v72, v72
	v_add_f32_e32 v68, 1.0, v68
	v_mul_f32_e32 v64, 0xbfb8aa3b, v64
	v_exp_f32_e32 v64, v64
	v_add_f32_e32 v72, 1.0, v72
	v_add_f32_e32 v64, 1.0, v64
	v_mul_f32_e32 v65, 0xbfb8aa3b, v65
	v_exp_f32_e32 v65, v65
	v_rcp_f32_e32 v77, v72
	v_mul_f32_e32 v72, 0xbfb8aa3b, v73
	v_exp_f32_e32 v72, v72
	v_add_f32_e32 v65, 1.0, v65
	v_pk_add_f32 v[70:71], v[70:71], v[22:23]
	v_pk_add_f32 v[66:67], v[66:67], v[18:19]
	v_add_f32_e32 v72, 1.0, v72
	v_mul_f32_e32 v66, 0xbfb8aa3b, v66
	v_exp_f32_e32 v66, v66
	v_mul_f32_e32 v67, 0xbfb8aa3b, v67
	v_rcp_f32_e32 v82, v72
	v_mul_f32_e32 v72, 0xbfb8aa3b, v78
	v_exp_f32_e32 v72, v72
	v_add_f32_e32 v66, 1.0, v66
	v_exp_f32_e32 v67, v67
	v_pk_add_f32 v[60:61], v[60:61], v[36:37]
	v_add_f32_e32 v72, 1.0, v72
	v_add_f32_e32 v67, 1.0, v67
	v_mul_f32_e32 v60, 0xbfb8aa3b, v60
	v_exp_f32_e32 v60, v60
	v_rcp_f32_e32 v78, v72
	v_mul_f32_e32 v72, 0xbfb8aa3b, v74
	v_exp_f32_e32 v72, v72
	v_add_f32_e32 v60, 1.0, v60
	v_pk_add_f32 v[56:57], v[56:57], v[32:33]
	v_pk_add_f32 v[62:63], v[62:63], v[38:39]
	v_add_f32_e32 v72, 1.0, v72
	v_mul_f32_e32 v56, 0xbfb8aa3b, v56
	v_exp_f32_e32 v56, v56
	v_pk_add_f32 v[58:59], v[58:59], v[34:35]
	v_rcp_f32_e32 v83, v72
	v_mul_f32_e32 v72, 0xbfb8aa3b, v79
	v_exp_f32_e32 v72, v72
	v_add_f32_e32 v56, 1.0, v56
	v_pk_add_f32 v[52:53], v[52:53], v[20:21]
	v_pk_add_f32 v[48:49], v[48:49], v[16:17]
	v_add_f32_e32 v72, 1.0, v72
	v_mul_f32_e32 v52, 0xbfb8aa3b, v52
	v_exp_f32_e32 v52, v52
	v_mul_f32_e32 v48, 0xbfb8aa3b, v48
	v_rcp_f32_e32 v79, v72
	v_mul_f32_e32 v72, 0xbfb8aa3b, v75
	v_exp_f32_e32 v72, v72
	v_add_f32_e32 v52, 1.0, v52
	v_exp_f32_e32 v48, v48
	v_mul_f32_e32 v49, 0xbfb8aa3b, v49
	v_add_f32_e32 v72, 1.0, v72
	v_add_f32_e32 v48, 1.0, v48
	v_exp_f32_e32 v49, v49
	v_pk_add_f32 v[54:55], v[54:55], v[22:23]
	v_rcp_f32_e32 v84, v72
	v_mad_i64_i32 v[72:73], s[18:19], v80, s11, v[136:137]
	v_lshl_add_u64 v[72:73], v[72:73], 0, v[138:139]
	v_cvt_pk_bf16_f32 v74, v76, v77
	v_cvt_pk_bf16_f32 v75, v78, v79
	v_cvt_pk_bf16_f32 v76, v81, v82
	v_cvt_pk_bf16_f32 v77, v83, v84
	global_store_dwordx4 v[72:73], v[74:77], off
	v_add_f32_e32 v49, 1.0, v49
	v_pk_add_f32 v[50:51], v[50:51], v[18:19]
	v_mul_f32_e32 v50, 0xbfb8aa3b, v50
	v_exp_f32_e32 v50, v50
	v_mul_f32_e32 v51, 0xbfb8aa3b, v51
	v_rcp_f32_e32 v68, v68
	v_add_f32_e32 v50, 1.0, v50
	v_exp_f32_e32 v51, v51
	v_rcp_f32_e32 v74, v64
	v_mul_f32_e32 v64, 0xbfb8aa3b, v69
	v_exp_f32_e32 v64, v64
	v_add_f32_e32 v51, 1.0, v51
	v_add_f32_e32 v64, 1.0, v64
	s_nop 0
	v_rcp_f32_e32 v64, v64
	s_nop 0
	v_cvt_pk_bf16_f32 v64, v68, v64
	s_nop 0
	v_rcp_f32_e32 v69, v65
	v_mul_f32_e32 v65, 0xbfb8aa3b, v70
	v_exp_f32_e32 v65, v65
	s_nop 0
	v_add_f32_e32 v65, 1.0, v65
	s_nop 0
	v_rcp_f32_e32 v65, v65
	s_nop 0
	v_rcp_f32_e32 v70, v66
	v_mul_f32_e32 v66, 0xbfb8aa3b, v71
	v_exp_f32_e32 v66, v66
	s_nop 0
	v_add_f32_e32 v66, 1.0, v66
	s_nop 0
	v_rcp_f32_e32 v66, v66
	s_nop 0
	v_cvt_pk_bf16_f32 v65, v65, v66
	v_cvt_pk_bf16_f32 v66, v74, v69
	s_nop 0
	v_rcp_f32_e32 v67, v67
	s_nop 0
	v_cvt_pk_bf16_f32 v67, v70, v67
	global_store_dwordx4 v[72:73], v[64:67], off offset:256
	s_nop 1
	s_nop 1
	v_add_u32_e32 v64, 0x90, v162
	v_rcp_f32_e32 v60, v60
	s_nop 0
	v_rcp_f32_e32 v65, v56
	v_mul_f32_e32 v56, 0xbfb8aa3b, v61
	v_exp_f32_e32 v56, v56
	s_nop 0
	v_add_f32_e32 v56, 1.0, v56
	s_nop 0
	v_rcp_f32_e32 v61, v56
	v_mul_f32_e32 v56, 0xbfb8aa3b, v57
	v_exp_f32_e32 v56, v56
	s_nop 0
	v_add_f32_e32 v56, 1.0, v56
	s_nop 0
	v_rcp_f32_e32 v66, v56
	v_mul_f32_e32 v56, 0xbfb8aa3b, v62
	v_exp_f32_e32 v56, v56
	s_nop 0
	v_add_f32_e32 v56, 1.0, v56
	s_nop 0
	v_rcp_f32_e32 v62, v56
	v_mul_f32_e32 v56, 0xbfb8aa3b, v58
	v_exp_f32_e32 v56, v56
	s_nop 0
	v_add_f32_e32 v56, 1.0, v56
	s_nop 0
	v_rcp_f32_e32 v67, v56
	v_mul_f32_e32 v56, 0xbfb8aa3b, v63
	v_exp_f32_e32 v56, v56
	s_nop 0
	v_add_f32_e32 v56, 1.0, v56
	s_nop 0
	v_rcp_f32_e32 v63, v56
	v_mul_f32_e32 v56, 0xbfb8aa3b, v59
	v_exp_f32_e32 v56, v56
	s_nop 0
	v_add_f32_e32 v56, 1.0, v56
	s_nop 0
	v_rcp_f32_e32 v68, v56
	v_mad_i64_i32 v[56:57], s[18:19], v64, s11, v[136:137]
	v_lshl_add_u64 v[56:57], v[56:57], 0, v[138:139]
	v_cvt_pk_bf16_f32 v58, v60, v61
	v_cvt_pk_bf16_f32 v59, v62, v63
	v_cvt_pk_bf16_f32 v60, v65, v66
	v_cvt_pk_bf16_f32 v61, v67, v68
	global_store_dwordx4 v[56:57], v[58:61], off
	s_nop 1
	s_nop 0
	v_rcp_f32_e32 v52, v52
	s_nop 0
	v_rcp_f32_e32 v58, v48
	v_mul_f32_e32 v48, 0xbfb8aa3b, v53
	v_exp_f32_e32 v48, v48
	s_nop 0
	v_add_f32_e32 v48, 1.0, v48
	s_nop 0
	v_rcp_f32_e32 v48, v48
	s_nop 0
	v_cvt_pk_bf16_f32 v48, v52, v48
	s_nop 0
	v_rcp_f32_e32 v53, v49
	v_mul_f32_e32 v49, 0xbfb8aa3b, v54
	v_exp_f32_e32 v49, v49
	s_nop 0
	v_add_f32_e32 v49, 1.0, v49
	s_nop 0
	v_rcp_f32_e32 v49, v49
	s_nop 0
	v_rcp_f32_e32 v54, v50
	v_mul_f32_e32 v50, 0xbfb8aa3b, v55
	v_exp_f32_e32 v50, v50
	s_nop 0
	v_add_f32_e32 v50, 1.0, v50
	s_nop 0
	v_rcp_f32_e32 v50, v50
	s_nop 0
	v_cvt_pk_bf16_f32 v49, v49, v50
	v_cvt_pk_bf16_f32 v50, v58, v53
	s_nop 0
	v_rcp_f32_e32 v51, v51
	s_nop 0
	v_cvt_pk_bf16_f32 v51, v54, v51
	global_store_dwordx4 v[56:57], v[48:51], off offset:256
	v_pk_add_f32 v[44:45], v[44:45], v[36:37]
	v_pk_add_f32 v[40:41], v[40:41], v[32:33]
	v_mul_f32_e32 v44, 0xbfb8aa3b, v44
	v_exp_f32_e32 v44, v44
	v_mul_f32_e32 v40, 0xbfb8aa3b, v40
	v_exp_f32_e32 v40, v40
	v_pk_add_f32 v[46:47], v[46:47], v[38:39]
	v_add_f32_e32 v44, 1.0, v44
	v_add_f32_e32 v40, 1.0, v40
	v_pk_add_f32 v[42:43], v[42:43], v[34:35]
	v_pk_add_f32 v[28:29], v[28:29], v[20:21]
	v_rcp_f32_e32 v44, v44
	v_mul_f32_e32 v28, 0xbfb8aa3b, v28
	v_exp_f32_e32 v28, v28
	v_add_u32_e32 v48, 0xa0, v162
	v_rcp_f32_e32 v49, v40
	v_mul_f32_e32 v40, 0xbfb8aa3b, v45
	v_exp_f32_e32 v40, v40
	v_add_f32_e32 v28, 1.0, v28
	v_pk_add_f32 v[24:25], v[24:25], v[16:17]
	v_pk_add_f32 v[30:31], v[30:31], v[22:23]
	v_add_f32_e32 v40, 1.0, v40
	v_mul_f32_e32 v24, 0xbfb8aa3b, v24
	v_exp_f32_e32 v24, v24
	v_mul_f32_e32 v25, 0xbfb8aa3b, v25
	v_rcp_f32_e32 v45, v40
	v_mul_f32_e32 v40, 0xbfb8aa3b, v41
	v_exp_f32_e32 v40, v40
	v_add_f32_e32 v24, 1.0, v24
	v_exp_f32_e32 v25, v25
	v_pk_add_f32 v[26:27], v[26:27], v[18:19]
	v_add_f32_e32 v40, 1.0, v40
	v_add_f32_e32 v25, 1.0, v25
	v_mul_f32_e32 v26, 0xbfb8aa3b, v26
	v_exp_f32_e32 v26, v26
	v_rcp_f32_e32 v50, v40
	v_mul_f32_e32 v40, 0xbfb8aa3b, v46
	v_exp_f32_e32 v40, v40
	v_add_f32_e32 v26, 1.0, v26
	v_mul_f32_e32 v27, 0xbfb8aa3b, v27
	v_exp_f32_e32 v27, v27
	v_add_f32_e32 v40, 1.0, v40
	v_add_f32_e32 v27, 1.0, v27
	v_pk_add_f32 v[12:13], v[12:13], v[36:37]
	v_pk_add_f32 v[8:9], v[8:9], v[32:33]
	v_rcp_f32_e32 v46, v40
	v_mul_f32_e32 v40, 0xbfb8aa3b, v42
	v_exp_f32_e32 v40, v40
	v_mul_f32_e32 v12, 0xbfb8aa3b, v12
	v_exp_f32_e32 v12, v12
	v_mul_f32_e32 v8, 0xbfb8aa3b, v8
	v_add_f32_e32 v40, 1.0, v40
	v_add_f32_e32 v12, 1.0, v12
	v_exp_f32_e32 v8, v8
	v_pk_add_f32 v[14:15], v[14:15], v[38:39]
	v_rcp_f32_e32 v51, v40
	v_mul_f32_e32 v40, 0xbfb8aa3b, v47
	v_exp_f32_e32 v40, v40
	v_add_f32_e32 v8, 1.0, v8
	v_pk_add_f32 v[10:11], v[10:11], v[34:35]
	v_pk_add_f32 v[4:5], v[4:5], v[20:21]
	v_add_f32_e32 v40, 1.0, v40
	v_mul_f32_e32 v4, 0xbfb8aa3b, v4
	v_exp_f32_e32 v4, v4
	v_pk_add_f32 v[0:1], v[0:1], v[16:17]
	v_rcp_f32_e32 v47, v40
	v_mul_f32_e32 v40, 0xbfb8aa3b, v43
	v_exp_f32_e32 v40, v40
	v_add_f32_e32 v4, 1.0, v4
	v_mul_f32_e32 v0, 0xbfb8aa3b, v0
	v_exp_f32_e32 v0, v0
	v_add_f32_e32 v40, 1.0, v40
	v_add_f32_e32 v0, 1.0, v0
	v_mul_f32_e32 v1, 0xbfb8aa3b, v1
	v_exp_f32_e32 v1, v1
	v_rcp_f32_e32 v52, v40
	v_mad_i64_i32 v[40:41], s[18:19], v48, s11, v[136:137]
	v_lshl_add_u64 v[40:41], v[40:41], 0, v[138:139]
	v_cvt_pk_bf16_f32 v42, v44, v45
	v_cvt_pk_bf16_f32 v43, v46, v47
	v_cvt_pk_bf16_f32 v44, v49, v50
	v_cvt_pk_bf16_f32 v45, v51, v52
	global_store_dwordx4 v[40:41], v[42:45], off
	v_add_f32_e32 v1, 1.0, v1
	v_pk_add_f32 v[6:7], v[6:7], v[22:23]
	v_pk_add_f32 v[2:3], v[2:3], v[18:19]
	v_rcp_f32_e32 v28, v28
	v_mul_f32_e32 v2, 0xbfb8aa3b, v2
	v_exp_f32_e32 v2, v2
	v_mul_f32_e32 v3, 0xbfb8aa3b, v3
	v_rcp_f32_e32 v42, v24
	v_mul_f32_e32 v24, 0xbfb8aa3b, v29
	v_exp_f32_e32 v24, v24
	v_add_f32_e32 v2, 1.0, v2
	v_exp_f32_e32 v3, v3
	v_add_f32_e32 v24, 1.0, v24
	v_add_f32_e32 v3, 1.0, v3
	v_rcp_f32_e32 v24, v24
	s_nop 0
	v_cvt_pk_bf16_f32 v24, v28, v24
	s_nop 0
	v_rcp_f32_e32 v29, v25
	v_mul_f32_e32 v25, 0xbfb8aa3b, v30
	v_exp_f32_e32 v25, v25
	s_nop 0
	v_add_f32_e32 v25, 1.0, v25
	s_nop 0
	v_rcp_f32_e32 v25, v25
	s_nop 0
	v_rcp_f32_e32 v30, v26
	v_mul_f32_e32 v26, 0xbfb8aa3b, v31
	v_exp_f32_e32 v26, v26
	s_nop 0
	v_add_f32_e32 v26, 1.0, v26
	s_nop 0
	v_rcp_f32_e32 v26, v26
	s_nop 0
	v_cvt_pk_bf16_f32 v25, v25, v26
	v_cvt_pk_bf16_f32 v26, v42, v29
	s_nop 0
	v_rcp_f32_e32 v27, v27
	s_nop 0
	v_cvt_pk_bf16_f32 v27, v30, v27
	global_store_dwordx4 v[40:41], v[24:27], off offset:256
	s_nop 1
	s_nop 1
	v_add_u32_e32 v24, 0xb0, v162
	v_rcp_f32_e32 v12, v12
	s_nop 0
	v_rcp_f32_e32 v25, v8
	v_mul_f32_e32 v8, 0xbfb8aa3b, v13
	v_exp_f32_e32 v8, v8
	s_nop 0
	v_add_f32_e32 v8, 1.0, v8
	s_nop 0
	v_rcp_f32_e32 v13, v8
	v_mul_f32_e32 v8, 0xbfb8aa3b, v9
	v_exp_f32_e32 v8, v8
	s_nop 0
	v_add_f32_e32 v8, 1.0, v8
	s_nop 0
	v_rcp_f32_e32 v26, v8
	v_mul_f32_e32 v8, 0xbfb8aa3b, v14
	v_exp_f32_e32 v8, v8
	s_nop 0
	v_add_f32_e32 v8, 1.0, v8
	s_nop 0
	v_rcp_f32_e32 v14, v8
	v_mul_f32_e32 v8, 0xbfb8aa3b, v10
	v_exp_f32_e32 v8, v8
	s_nop 0
	v_add_f32_e32 v8, 1.0, v8
	s_nop 0
	v_rcp_f32_e32 v27, v8
	v_mul_f32_e32 v8, 0xbfb8aa3b, v15
	v_exp_f32_e32 v8, v8
	s_nop 0
	v_add_f32_e32 v8, 1.0, v8
	s_nop 0
	v_rcp_f32_e32 v15, v8
	v_mul_f32_e32 v8, 0xbfb8aa3b, v11
	v_exp_f32_e32 v8, v8
	s_nop 0
	v_add_f32_e32 v8, 1.0, v8
	s_nop 0
	v_rcp_f32_e32 v28, v8
	v_mad_i64_i32 v[8:9], s[18:19], v24, s11, v[136:137]
	v_lshl_add_u64 v[8:9], v[8:9], 0, v[138:139]
	v_cvt_pk_bf16_f32 v10, v12, v13
	v_cvt_pk_bf16_f32 v11, v14, v15
	v_cvt_pk_bf16_f32 v12, v25, v26
	v_cvt_pk_bf16_f32 v13, v27, v28
	global_store_dwordx4 v[8:9], v[10:13], off
	s_nop 1
	s_nop 0
	v_rcp_f32_e32 v4, v4
	s_nop 0
	v_rcp_f32_e32 v10, v0
	v_mul_f32_e32 v0, 0xbfb8aa3b, v5
	v_exp_f32_e32 v0, v0
	s_nop 0
	v_add_f32_e32 v0, 1.0, v0
	s_nop 0
	v_rcp_f32_e32 v0, v0
	s_nop 0
	v_cvt_pk_bf16_f32 v0, v4, v0
	s_nop 0
	v_rcp_f32_e32 v5, v1
	v_mul_f32_e32 v1, 0xbfb8aa3b, v6
	v_exp_f32_e32 v1, v1
	s_nop 0
	v_add_f32_e32 v1, 1.0, v1
	s_nop 0
	v_rcp_f32_e32 v1, v1
	s_nop 0
	v_rcp_f32_e32 v6, v2
	v_mul_f32_e32 v2, 0xbfb8aa3b, v7
	v_exp_f32_e32 v2, v2
	s_nop 0
	v_add_f32_e32 v2, 1.0, v2
	s_nop 0
	v_rcp_f32_e32 v2, v2
	s_nop 0
	v_cvt_pk_bf16_f32 v1, v1, v2
	v_cvt_pk_bf16_f32 v2, v10, v5
	s_nop 0
	v_rcp_f32_e32 v3, v3
	s_nop 0
	v_cvt_pk_bf16_f32 v3, v6, v3
	global_store_dwordx4 v[8:9], v[0:3], off offset:256
	s_andn2_b64 vcc, exec, s[38:39]
	s_mov_b64 s[18:19], -1
	s_cbranch_vccnz .LBB0_1093
	s_andn2_b64 vcc, exec, s[2:3]
	s_cbranch_vccnz .LBB0_1092
	s_barrier
	s_branch .LBB0_1092
